# K-loops: priority raised before the block-entry barrier, duplicate lgkmcnt(0) and mid-block setprio toggles removed (on top of P0 task spread)
# speedup vs baseline: 1.0115x; 1.0048x over previous
.LBB0_384:
	ds_read_b128 v[134:137], v199
	ds_read_b128 v[138:141], v200
	ds_read_b128 v[142:145], v201
	ds_read_b128 v[146:149], v202
	ds_read_b128 v[150:153], v203
	ds_read_b128 v[174:177], v204
	ds_read_b128 v[178:181], v205
	ds_read_b128 v[182:185], v206
	s_add_u32 s24, s4, vcc_lo
	s_addc_u32 s25, s5, vcc_hi
	s_add_u32 s24, s24, 0x100
	s_addc_u32 s25, s25, 0
	s_add_u32 s82, s39, vcc_lo
	s_addc_u32 s83, s67, vcc_hi
	s_cmpk_eq_i32 vcc_lo, 0x700
	s_cselect_b32 s87, s29, s83
	s_cselect_b32 s86, s38, s82
	s_cselect_b32 s83, s34, s25
	s_cselect_b32 s82, s35, s24
	v_lshl_add_u64 v[154:155], v[132:133], 0, vcc
	v_lshl_add_u64 v[250:251], v[154:155], 0, s[48:49]
	s_add_i32 m0, s79, 0x8000
	s_mov_b64 s[24:25], 0x20080
	ds_read_b128 v[218:221], v207
	ds_read_b128 v[222:225], v207 offset:2048
	ds_read_b128 v[226:229], v208
	ds_read_b128 v[230:233], v208 offset:2048
	ds_read_b128 v[234:237], v207 offset:4096
	ds_read_b128 v[238:241], v207 offset:6144
	ds_read_b128 v[242:245], v208 offset:4096
	ds_read_b128 v[246:249], v208 offset:6144
	global_load_lds_dwordx4 v[250:251], off
	v_lshl_add_u64 v[250:251], v[154:155], 0, s[24:25]
	s_add_i32 m0, s79, 0xa000
	s_mov_b64 s[24:25], 0x60080
	global_load_lds_dwordx4 v[250:251], off
	v_lshl_add_u64 v[250:251], v[154:155], 0, s[50:51]
	s_add_i32 m0, s79, 0xc000
	v_lshl_add_u64 v[154:155], v[154:155], 0, s[24:25]
	global_load_lds_dwordx4 v[250:251], off
	s_add_i32 m0, s79, 0xe000
	s_nop 0
	global_load_lds_dwordx4 v[154:155], off
	s_waitcnt vmcnt(8)
	s_waitcnt lgkmcnt(0)
	s_setprio 1
	s_barrier
	v_mfma_f32_16x16x32_bf16 v[128:131], v[134:137], v[218:221], v[128:131]
	v_mfma_f32_16x16x32_bf16 v[124:127], v[142:145], v[218:221], v[124:127]
	v_mfma_f32_16x16x32_bf16 v[112:115], v[134:137], v[222:225], v[112:115]
	v_mfma_f32_16x16x32_bf16 v[108:111], v[142:145], v[222:225], v[108:111]
	v_mfma_f32_16x16x32_bf16 v[96:99], v[134:137], v[234:237], v[96:99]
	v_mfma_f32_16x16x32_bf16 v[92:95], v[142:145], v[234:237], v[92:95]
	v_mfma_f32_16x16x32_bf16 v[80:83], v[134:137], v[238:241], v[80:83]
	v_mfma_f32_16x16x32_bf16 v[76:79], v[142:145], v[238:241], v[76:79]
	v_mfma_f32_16x16x32_bf16 v[128:131], v[138:141], v[226:229], v[128:131]
	v_mfma_f32_16x16x32_bf16 v[124:127], v[146:149], v[226:229], v[124:127]
	v_mfma_f32_16x16x32_bf16 v[112:115], v[138:141], v[230:233], v[112:115]
	v_mfma_f32_16x16x32_bf16 v[108:111], v[146:149], v[230:233], v[108:111]
	v_mfma_f32_16x16x32_bf16 v[96:99], v[138:141], v[242:245], v[96:99]
	v_mfma_f32_16x16x32_bf16 v[92:95], v[146:149], v[242:245], v[92:95]
	v_mfma_f32_16x16x32_bf16 v[80:83], v[138:141], v[246:249], v[80:83]
	v_mfma_f32_16x16x32_bf16 v[76:79], v[146:149], v[246:249], v[76:79]
	v_mfma_f32_16x16x32_bf16 v[120:123], v[150:153], v[218:221], v[120:123]
	v_mfma_f32_16x16x32_bf16 v[116:119], v[178:181], v[218:221], v[116:119]
	v_mfma_f32_16x16x32_bf16 v[104:107], v[150:153], v[222:225], v[104:107]
	v_mfma_f32_16x16x32_bf16 v[100:103], v[178:181], v[222:225], v[100:103]
	v_mfma_f32_16x16x32_bf16 v[88:91], v[150:153], v[234:237], v[88:91]
	v_mfma_f32_16x16x32_bf16 v[84:87], v[178:181], v[234:237], v[84:87]
	v_mfma_f32_16x16x32_bf16 v[72:75], v[150:153], v[238:241], v[72:75]
	v_mfma_f32_16x16x32_bf16 v[68:71], v[178:181], v[238:241], v[68:71]
	v_mfma_f32_16x16x32_bf16 v[120:123], v[174:177], v[226:229], v[120:123]
	v_mfma_f32_16x16x32_bf16 v[116:119], v[182:185], v[226:229], v[116:119]
	v_mfma_f32_16x16x32_bf16 v[104:107], v[174:177], v[230:233], v[104:107]
	v_mfma_f32_16x16x32_bf16 v[100:103], v[182:185], v[230:233], v[100:103]
	v_mfma_f32_16x16x32_bf16 v[88:91], v[174:177], v[242:245], v[88:91]
	v_mfma_f32_16x16x32_bf16 v[84:87], v[182:185], v[242:245], v[84:87]
	v_mfma_f32_16x16x32_bf16 v[72:75], v[174:177], v[246:249], v[72:75]
	v_mfma_f32_16x16x32_bf16 v[68:71], v[182:185], v[246:249], v[68:71]
	s_setprio 0
	s_barrier
	s_add_i32 s24, s1, s77
	v_lshl_add_u64 v[154:155], s[86:87], 0, v[158:159]
	s_mov_b32 m0, s24
	ds_read_b128 v[218:221], v207 offset:16384
	ds_read_b128 v[222:225], v207 offset:18432
	ds_read_b128 v[226:229], v208 offset:16384
	ds_read_b128 v[230:233], v208 offset:18432
	ds_read_b128 v[234:237], v207 offset:20480
	ds_read_b128 v[238:241], v207 offset:22528
	ds_read_b128 v[242:245], v208 offset:20480
	ds_read_b128 v[246:249], v208 offset:22528
	global_load_lds_dwordx4 v[154:155], off
	v_lshl_add_u64 v[250:251], v[154:155], 0, s[14:15]
	s_add_i32 m0, s24, 0x2000
	s_add_i32 s24, s12, s77
	global_load_lds_dwordx4 v[250:251], off
	v_lshl_add_u64 v[250:251], v[154:155], 0, s[16:17]
	s_mov_b32 m0, s24
	s_nop 0
	global_load_lds_dwordx4 v[250:251], off
	v_lshl_add_u64 v[250:251], v[154:155], 0, s[18:19]
	s_add_i32 m0, s24, 0x2000
	s_nop 0
	global_load_lds_dwordx4 v[250:251], off
	s_waitcnt vmcnt(4)
	s_waitcnt lgkmcnt(0)
	s_setprio 1
	s_barrier
	v_mfma_f32_16x16x32_bf16 v[64:67], v[134:137], v[218:221], v[64:67]
	v_mfma_f32_16x16x32_bf16 v[60:63], v[142:145], v[218:221], v[60:63]
	v_mfma_f32_16x16x32_bf16 v[48:51], v[134:137], v[222:225], v[48:51]
	v_mfma_f32_16x16x32_bf16 v[44:47], v[142:145], v[222:225], v[44:47]
	v_mfma_f32_16x16x32_bf16 v[32:35], v[134:137], v[234:237], v[32:35]
	v_mfma_f32_16x16x32_bf16 v[28:31], v[142:145], v[234:237], v[28:31]
	v_mfma_f32_16x16x32_bf16 v[16:19], v[134:137], v[238:241], v[16:19]
	v_mfma_f32_16x16x32_bf16 v[12:15], v[142:145], v[238:241], v[12:15]
	v_mfma_f32_16x16x32_bf16 v[64:67], v[138:141], v[226:229], v[64:67]
	v_mfma_f32_16x16x32_bf16 v[60:63], v[146:149], v[226:229], v[60:63]
	v_mfma_f32_16x16x32_bf16 v[48:51], v[138:141], v[230:233], v[48:51]
	v_mfma_f32_16x16x32_bf16 v[44:47], v[146:149], v[230:233], v[44:47]
	v_mfma_f32_16x16x32_bf16 v[32:35], v[138:141], v[242:245], v[32:35]
	v_mfma_f32_16x16x32_bf16 v[28:31], v[146:149], v[242:245], v[28:31]
	v_mfma_f32_16x16x32_bf16 v[16:19], v[138:141], v[246:249], v[16:19]
	v_mfma_f32_16x16x32_bf16 v[12:15], v[146:149], v[246:249], v[12:15]
	v_mfma_f32_16x16x32_bf16 v[56:59], v[150:153], v[218:221], v[56:59]
	v_mfma_f32_16x16x32_bf16 v[52:55], v[178:181], v[218:221], v[52:55]
	v_mfma_f32_16x16x32_bf16 v[40:43], v[150:153], v[222:225], v[40:43]
	v_mfma_f32_16x16x32_bf16 v[36:39], v[178:181], v[222:225], v[36:39]
	v_mfma_f32_16x16x32_bf16 v[24:27], v[150:153], v[234:237], v[24:27]
	v_mfma_f32_16x16x32_bf16 v[20:23], v[178:181], v[234:237], v[20:23]
	v_mfma_f32_16x16x32_bf16 v[8:11], v[150:153], v[238:241], v[8:11]
	v_mfma_f32_16x16x32_bf16 v[4:7], v[178:181], v[238:241], v[4:7]
	v_mfma_f32_16x16x32_bf16 v[56:59], v[174:177], v[226:229], v[56:59]
	v_mfma_f32_16x16x32_bf16 v[52:55], v[182:185], v[226:229], v[52:55]
	v_mfma_f32_16x16x32_bf16 v[40:43], v[174:177], v[230:233], v[40:43]
	v_mfma_f32_16x16x32_bf16 v[36:39], v[182:185], v[230:233], v[36:39]
	v_mfma_f32_16x16x32_bf16 v[24:27], v[174:177], v[242:245], v[24:27]
	v_mfma_f32_16x16x32_bf16 v[20:23], v[182:185], v[242:245], v[20:23]
	v_mfma_f32_16x16x32_bf16 v[8:11], v[174:177], v[246:249], v[8:11]
	v_mfma_f32_16x16x32_bf16 v[4:7], v[182:185], v[246:249], v[4:7]
	s_setprio 0
	s_barrier
	ds_read_b128 v[134:137], v213
	ds_read_b128 v[138:141], v214
	ds_read_b128 v[142:145], v209
	ds_read_b128 v[146:149], v210
	ds_read_b128 v[150:153], v215
	ds_read_b128 v[174:177], v216
	ds_read_b128 v[178:181], v211
	ds_read_b128 v[182:185], v212
	s_mov_b32 m0, s79
	v_lshl_add_u64 v[250:251], s[82:83], 0, v[0:1]
	ds_read_b128 v[218:221], v207 offset:32768
	ds_read_b128 v[222:225], v207 offset:34816
	ds_read_b128 v[226:229], v208 offset:32768
	ds_read_b128 v[230:233], v208 offset:34816
	ds_read_b128 v[234:237], v207 offset:36864
	ds_read_b128 v[238:241], v207 offset:38912
	ds_read_b128 v[242:245], v208 offset:36864
	ds_read_b128 v[246:249], v208 offset:38912
	global_load_lds_dwordx4 v[250:251], off
	v_lshl_add_u64 v[252:253], v[250:251], 0, s[20:21]
	s_mov_b32 m0, s81
	s_nop 0
	global_load_lds_dwordx4 v[252:253], off
	v_lshl_add_u64 v[252:253], v[250:251], 0, s[14:15]
	s_mov_b32 m0, s97
	v_lshl_add_u64 v[250:251], v[250:251], 0, s[22:23]
	global_load_lds_dwordx4 v[252:253], off
	s_mov_b32 m0, s64
	s_nop 0
	global_load_lds_dwordx4 v[250:251], off
	s_waitcnt vmcnt(8)
	s_waitcnt lgkmcnt(0)
	s_setprio 1
	s_barrier
	v_mfma_f32_16x16x32_bf16 v[128:131], v[134:137], v[218:221], v[128:131]
	v_mfma_f32_16x16x32_bf16 v[124:127], v[142:145], v[218:221], v[124:127]
	v_mfma_f32_16x16x32_bf16 v[112:115], v[134:137], v[222:225], v[112:115]
	v_mfma_f32_16x16x32_bf16 v[108:111], v[142:145], v[222:225], v[108:111]
	v_mfma_f32_16x16x32_bf16 v[96:99], v[134:137], v[234:237], v[96:99]
	v_mfma_f32_16x16x32_bf16 v[92:95], v[142:145], v[234:237], v[92:95]
	v_mfma_f32_16x16x32_bf16 v[80:83], v[134:137], v[238:241], v[80:83]
	v_mfma_f32_16x16x32_bf16 v[76:79], v[142:145], v[238:241], v[76:79]
	v_mfma_f32_16x16x32_bf16 v[128:131], v[138:141], v[226:229], v[128:131]
	v_mfma_f32_16x16x32_bf16 v[124:127], v[146:149], v[226:229], v[124:127]
	v_mfma_f32_16x16x32_bf16 v[112:115], v[138:141], v[230:233], v[112:115]
	v_mfma_f32_16x16x32_bf16 v[108:111], v[146:149], v[230:233], v[108:111]
	v_mfma_f32_16x16x32_bf16 v[96:99], v[138:141], v[242:245], v[96:99]
	v_mfma_f32_16x16x32_bf16 v[92:95], v[146:149], v[242:245], v[92:95]
	v_mfma_f32_16x16x32_bf16 v[80:83], v[138:141], v[246:249], v[80:83]
	v_mfma_f32_16x16x32_bf16 v[76:79], v[146:149], v[246:249], v[76:79]
	v_mfma_f32_16x16x32_bf16 v[120:123], v[150:153], v[218:221], v[120:123]
	v_mfma_f32_16x16x32_bf16 v[116:119], v[178:181], v[218:221], v[116:119]
	v_mfma_f32_16x16x32_bf16 v[104:107], v[150:153], v[222:225], v[104:107]
	v_mfma_f32_16x16x32_bf16 v[100:103], v[178:181], v[222:225], v[100:103]
	v_mfma_f32_16x16x32_bf16 v[88:91], v[150:153], v[234:237], v[88:91]
	v_mfma_f32_16x16x32_bf16 v[84:87], v[178:181], v[234:237], v[84:87]
	v_mfma_f32_16x16x32_bf16 v[72:75], v[150:153], v[238:241], v[72:75]
	v_mfma_f32_16x16x32_bf16 v[68:71], v[178:181], v[238:241], v[68:71]
	v_mfma_f32_16x16x32_bf16 v[120:123], v[174:177], v[226:229], v[120:123]
	v_mfma_f32_16x16x32_bf16 v[116:119], v[182:185], v[226:229], v[116:119]
	v_mfma_f32_16x16x32_bf16 v[104:107], v[174:177], v[230:233], v[104:107]
	v_mfma_f32_16x16x32_bf16 v[100:103], v[182:185], v[230:233], v[100:103]
	v_mfma_f32_16x16x32_bf16 v[88:91], v[174:177], v[242:245], v[88:91]
	v_mfma_f32_16x16x32_bf16 v[84:87], v[182:185], v[242:245], v[84:87]
	v_mfma_f32_16x16x32_bf16 v[72:75], v[174:177], v[246:249], v[72:75]
	v_mfma_f32_16x16x32_bf16 v[68:71], v[182:185], v[246:249], v[68:71]
	s_setprio 0
	s_barrier
	s_add_i32 s24, s70, s77
	v_lshl_add_u64 v[250:251], v[154:155], 0, s[48:49]
	s_mov_b32 m0, s24
	ds_read_b128 v[218:221], v207 offset:49152
	ds_read_b128 v[222:225], v207 offset:51200
	ds_read_b128 v[226:229], v208 offset:49152
	ds_read_b128 v[230:233], v208 offset:51200
	ds_read_b128 v[234:237], v207 offset:53248
	ds_read_b128 v[238:241], v207 offset:55296
	ds_read_b128 v[242:245], v208 offset:53248
	ds_read_b128 v[246:249], v208 offset:55296
	global_load_lds_dwordx4 v[250:251], off
	v_lshl_add_u64 v[250:251], v[154:155], 0, s[50:51]
	s_add_i32 m0, s24, 0x2000
	s_add_i32 s24, s71, s77
	global_load_lds_dwordx4 v[250:251], off
	v_lshl_add_u64 v[250:251], v[154:155], 0, s[52:53]
	s_mov_b32 m0, s24
	v_lshl_add_u64 v[154:155], v[154:155], 0, s[54:55]
	global_load_lds_dwordx4 v[250:251], off
	s_add_i32 m0, s24, 0x2000
	s_nop 0
	global_load_lds_dwordx4 v[154:155], off
	s_waitcnt vmcnt(4)
	s_waitcnt lgkmcnt(0)
	s_setprio 1
	s_barrier
	v_mfma_f32_16x16x32_bf16 v[64:67], v[134:137], v[218:221], v[64:67]
	v_mfma_f32_16x16x32_bf16 v[60:63], v[142:145], v[218:221], v[60:63]
	v_mfma_f32_16x16x32_bf16 v[48:51], v[134:137], v[222:225], v[48:51]
	v_mfma_f32_16x16x32_bf16 v[44:47], v[142:145], v[222:225], v[44:47]
	v_mfma_f32_16x16x32_bf16 v[32:35], v[134:137], v[234:237], v[32:35]
	v_mfma_f32_16x16x32_bf16 v[28:31], v[142:145], v[234:237], v[28:31]
	v_mfma_f32_16x16x32_bf16 v[16:19], v[134:137], v[238:241], v[16:19]
	v_mfma_f32_16x16x32_bf16 v[12:15], v[142:145], v[238:241], v[12:15]
	v_mfma_f32_16x16x32_bf16 v[64:67], v[138:141], v[226:229], v[64:67]
	v_mfma_f32_16x16x32_bf16 v[60:63], v[146:149], v[226:229], v[60:63]
	v_mfma_f32_16x16x32_bf16 v[48:51], v[138:141], v[230:233], v[48:51]
	v_mfma_f32_16x16x32_bf16 v[44:47], v[146:149], v[230:233], v[44:47]
	v_mfma_f32_16x16x32_bf16 v[32:35], v[138:141], v[242:245], v[32:35]
	v_mfma_f32_16x16x32_bf16 v[28:31], v[146:149], v[242:245], v[28:31]
	v_mfma_f32_16x16x32_bf16 v[16:19], v[138:141], v[246:249], v[16:19]
	v_mfma_f32_16x16x32_bf16 v[12:15], v[146:149], v[246:249], v[12:15]
	v_mfma_f32_16x16x32_bf16 v[56:59], v[150:153], v[218:221], v[56:59]
	v_mfma_f32_16x16x32_bf16 v[52:55], v[178:181], v[218:221], v[52:55]
	v_mfma_f32_16x16x32_bf16 v[40:43], v[150:153], v[222:225], v[40:43]
	v_mfma_f32_16x16x32_bf16 v[36:39], v[178:181], v[222:225], v[36:39]
	v_mfma_f32_16x16x32_bf16 v[24:27], v[150:153], v[234:237], v[24:27]
	v_mfma_f32_16x16x32_bf16 v[20:23], v[178:181], v[234:237], v[20:23]
	v_mfma_f32_16x16x32_bf16 v[8:11], v[150:153], v[238:241], v[8:11]
	v_mfma_f32_16x16x32_bf16 v[4:7], v[178:181], v[238:241], v[4:7]
	v_mfma_f32_16x16x32_bf16 v[56:59], v[174:177], v[226:229], v[56:59]
	v_mfma_f32_16x16x32_bf16 v[52:55], v[182:185], v[226:229], v[52:55]
	v_mfma_f32_16x16x32_bf16 v[40:43], v[174:177], v[230:233], v[40:43]
	v_mfma_f32_16x16x32_bf16 v[36:39], v[182:185], v[230:233], v[36:39]
	v_mfma_f32_16x16x32_bf16 v[24:27], v[174:177], v[242:245], v[24:27]
	v_mfma_f32_16x16x32_bf16 v[20:23], v[182:185], v[242:245], v[20:23]
	v_mfma_f32_16x16x32_bf16 v[8:11], v[174:177], v[246:249], v[8:11]
	v_mfma_f32_16x16x32_bf16 v[4:7], v[182:185], v[246:249], v[4:7]
	s_setprio 0
	s_barrier
	s_add_i32 s94, s94, 2
	s_add_u32 vcc_lo, vcc_lo, 0x100
	s_addc_u32 vcc_hi, vcc_hi, 0
	s_cmp_gt_u32 s94, 13
	s_cbranch_scc0 .LBB0_384
	s_and_b64 vcc, exec, s[56:57]
	s_cbranch_vccz .LBB0_387
	s_barrier

.LBB0_779:
	v_add_u32_e32 v4, s73, v159
	v_add_u32_e32 v6, s73, v173
	ds_read_b128 v[136:139], v4
	ds_read_b128 v[140:143], v6
	v_add_u32_e32 v4, s77, v159
	s_add_u32 s26, s28, s64
	v_add_u32_e32 v6, s77, v173
	ds_read_b128 v[180:183], v4
	ds_read_b128 v[196:199], v6
	v_add_u32_e32 v4, s79, v159
	s_addc_u32 s27, s29, s65
	v_add_u32_e32 v6, s79, v173
	ds_read_b128 v[200:203], v4
	ds_read_b128 v[204:207], v6
	v_add_u32_e32 v4, s80, v159
	s_add_u32 s26, s26, 0x100
	v_add_u32_e32 v6, s80, v173
	ds_read_b128 v[208:211], v4
	ds_read_b128 v[212:215], v6
	s_addc_u32 s27, s27, 0
	s_add_u32 s34, s93, s64
	s_addc_u32 s35, s94, s65
	s_cmpk_eq_i32 s64, 0xb00
	s_cselect_b32 s35, s63, s35
	s_cselect_b32 s34, s62, s34
	s_cselect_b32 s27, s1, s27
	s_cselect_b32 s26, s0, s26
	v_lshl_add_u64 v[6:7], v[170:171], 0, s[64:65]
	v_lshl_add_u64 v[184:185], v[6:7], 0, s[24:25]
	s_add_i32 m0, s66, 0x8000
	s_mov_b64 s[38:39], 0x30080
	ds_read_b128 v[216:219], v176
	ds_read_b128 v[220:223], v176 offset:2048
	ds_read_b128 v[224:227], v177
	ds_read_b128 v[228:231], v177 offset:2048
	ds_read_b128 v[232:235], v176 offset:4096
	ds_read_b128 v[236:239], v176 offset:6144
	ds_read_b128 v[240:243], v177 offset:4096
	ds_read_b128 v[244:247], v177 offset:6144
	global_load_lds_dwordx4 v[184:185], off
	v_lshl_add_u64 v[184:185], v[6:7], 0, s[38:39]
	s_add_i32 m0, s66, 0xa000
	s_mov_b64 s[38:39], 0x90080
	global_load_lds_dwordx4 v[184:185], off
	v_lshl_add_u64 v[184:185], v[6:7], 0, s[50:51]
	s_add_i32 m0, s66, 0xc000
	v_lshl_add_u64 v[6:7], v[6:7], 0, s[38:39]
	global_load_lds_dwordx4 v[184:185], off
	s_add_i32 m0, s66, 0xe000
	s_nop 0
	global_load_lds_dwordx4 v[6:7], off
	s_waitcnt vmcnt(8)
	s_waitcnt lgkmcnt(0)
	s_setprio 1
	s_barrier
	v_mfma_f32_16x16x32_bf16 v[132:135], v[136:139], v[216:219], v[132:135]
	v_mfma_f32_16x16x32_bf16 v[128:131], v[180:183], v[216:219], v[128:131]
	v_mfma_f32_16x16x32_bf16 v[116:119], v[136:139], v[220:223], v[116:119]
	v_mfma_f32_16x16x32_bf16 v[112:115], v[180:183], v[220:223], v[112:115]
	v_mfma_f32_16x16x32_bf16 v[100:103], v[136:139], v[232:235], v[100:103]
	v_mfma_f32_16x16x32_bf16 v[96:99], v[180:183], v[232:235], v[96:99]
	v_mfma_f32_16x16x32_bf16 v[84:87], v[136:139], v[236:239], v[84:87]
	v_mfma_f32_16x16x32_bf16 v[80:83], v[180:183], v[236:239], v[80:83]
	v_mfma_f32_16x16x32_bf16 v[132:135], v[140:143], v[224:227], v[132:135]
	v_mfma_f32_16x16x32_bf16 v[128:131], v[196:199], v[224:227], v[128:131]
	v_mfma_f32_16x16x32_bf16 v[116:119], v[140:143], v[228:231], v[116:119]
	v_mfma_f32_16x16x32_bf16 v[112:115], v[196:199], v[228:231], v[112:115]
	v_mfma_f32_16x16x32_bf16 v[100:103], v[140:143], v[240:243], v[100:103]
	v_mfma_f32_16x16x32_bf16 v[96:99], v[196:199], v[240:243], v[96:99]
	v_mfma_f32_16x16x32_bf16 v[84:87], v[140:143], v[244:247], v[84:87]
	v_mfma_f32_16x16x32_bf16 v[80:83], v[196:199], v[244:247], v[80:83]
	v_mfma_f32_16x16x32_bf16 v[124:127], v[200:203], v[216:219], v[124:127]
	v_mfma_f32_16x16x32_bf16 v[120:123], v[208:211], v[216:219], v[120:123]
	v_mfma_f32_16x16x32_bf16 v[108:111], v[200:203], v[220:223], v[108:111]
	v_mfma_f32_16x16x32_bf16 v[104:107], v[208:211], v[220:223], v[104:107]
	v_mfma_f32_16x16x32_bf16 v[92:95], v[200:203], v[232:235], v[92:95]
	v_mfma_f32_16x16x32_bf16 v[88:91], v[208:211], v[232:235], v[88:91]
	v_mfma_f32_16x16x32_bf16 v[76:79], v[200:203], v[236:239], v[76:79]
	v_mfma_f32_16x16x32_bf16 v[72:75], v[208:211], v[236:239], v[72:75]
	v_mfma_f32_16x16x32_bf16 v[124:127], v[204:207], v[224:227], v[124:127]
	v_mfma_f32_16x16x32_bf16 v[120:123], v[212:215], v[224:227], v[120:123]
	v_mfma_f32_16x16x32_bf16 v[108:111], v[204:207], v[228:231], v[108:111]
	v_mfma_f32_16x16x32_bf16 v[104:107], v[212:215], v[228:231], v[104:107]
	v_mfma_f32_16x16x32_bf16 v[92:95], v[204:207], v[240:243], v[92:95]
	v_mfma_f32_16x16x32_bf16 v[88:91], v[212:215], v[240:243], v[88:91]
	v_mfma_f32_16x16x32_bf16 v[76:79], v[204:207], v[244:247], v[76:79]
	v_mfma_f32_16x16x32_bf16 v[72:75], v[212:215], v[244:247], v[72:75]
	s_setprio 0
	s_barrier
	v_lshl_add_u64 v[184:185], s[34:35], 0, v[146:147]
	s_add_i32 s34, s73, s3
	s_mov_b32 m0, s34
	ds_read_b128 v[216:219], v176 offset:16384
	ds_read_b128 v[220:223], v176 offset:18432
	ds_read_b128 v[224:227], v177 offset:16384
	ds_read_b128 v[228:231], v177 offset:18432
	ds_read_b128 v[232:235], v176 offset:20480
	ds_read_b128 v[236:239], v176 offset:22528
	ds_read_b128 v[240:243], v177 offset:20480
	ds_read_b128 v[244:247], v177 offset:22528
	global_load_lds_dwordx4 v[184:185], off
	v_lshl_add_u64 v[6:7], v[184:185], 0, s[12:13]
	s_add_i32 m0, s34, 0x2000
	s_add_i32 s34, s79, s3
	global_load_lds_dwordx4 v[6:7], off
	v_lshl_add_u64 v[6:7], v[184:185], 0, s[14:15]
	s_mov_b32 m0, s34
	s_nop 0
	global_load_lds_dwordx4 v[6:7], off
	v_lshl_add_u64 v[6:7], v[184:185], 0, s[16:17]
	s_add_i32 m0, s34, 0x2000
	s_nop 0
	global_load_lds_dwordx4 v[6:7], off
	s_waitcnt vmcnt(4)
	s_waitcnt lgkmcnt(0)
	s_setprio 1
	s_barrier
	v_mfma_f32_16x16x32_bf16 v[68:71], v[136:139], v[216:219], v[68:71]
	v_mfma_f32_16x16x32_bf16 v[64:67], v[180:183], v[216:219], v[64:67]
	v_mfma_f32_16x16x32_bf16 v[52:55], v[136:139], v[220:223], v[52:55]
	v_mfma_f32_16x16x32_bf16 v[48:51], v[180:183], v[220:223], v[48:51]
	v_mfma_f32_16x16x32_bf16 v[36:39], v[136:139], v[232:235], v[36:39]
	v_mfma_f32_16x16x32_bf16 v[32:35], v[180:183], v[232:235], v[32:35]
	v_mfma_f32_16x16x32_bf16 v[20:23], v[136:139], v[236:239], v[20:23]
	v_mfma_f32_16x16x32_bf16 v[16:19], v[180:183], v[236:239], v[16:19]
	v_mfma_f32_16x16x32_bf16 v[68:71], v[140:143], v[224:227], v[68:71]
	v_mfma_f32_16x16x32_bf16 v[64:67], v[196:199], v[224:227], v[64:67]
	v_mfma_f32_16x16x32_bf16 v[52:55], v[140:143], v[228:231], v[52:55]
	v_mfma_f32_16x16x32_bf16 v[48:51], v[196:199], v[228:231], v[48:51]
	v_mfma_f32_16x16x32_bf16 v[36:39], v[140:143], v[240:243], v[36:39]
	v_mfma_f32_16x16x32_bf16 v[32:35], v[196:199], v[240:243], v[32:35]
	v_mfma_f32_16x16x32_bf16 v[20:23], v[140:143], v[244:247], v[20:23]
	v_mfma_f32_16x16x32_bf16 v[16:19], v[196:199], v[244:247], v[16:19]
	v_mfma_f32_16x16x32_bf16 v[60:63], v[200:203], v[216:219], v[60:63]
	v_mfma_f32_16x16x32_bf16 v[56:59], v[208:211], v[216:219], v[56:59]
	v_mfma_f32_16x16x32_bf16 v[44:47], v[200:203], v[220:223], v[44:47]
	v_mfma_f32_16x16x32_bf16 v[40:43], v[208:211], v[220:223], v[40:43]
	v_mfma_f32_16x16x32_bf16 v[28:31], v[200:203], v[232:235], v[28:31]
	v_mfma_f32_16x16x32_bf16 v[24:27], v[208:211], v[232:235], v[24:27]
	v_mfma_f32_16x16x32_bf16 v[12:15], v[200:203], v[236:239], v[12:15]
	v_mfma_f32_16x16x32_bf16 v[6:9], v[208:211], v[236:239], v[8:11]
	v_mfma_f32_16x16x32_bf16 v[60:63], v[204:207], v[224:227], v[60:63]
	v_mfma_f32_16x16x32_bf16 v[56:59], v[212:215], v[224:227], v[56:59]
	v_mfma_f32_16x16x32_bf16 v[44:47], v[204:207], v[228:231], v[44:47]
	v_mfma_f32_16x16x32_bf16 v[40:43], v[212:215], v[228:231], v[40:43]
	v_mfma_f32_16x16x32_bf16 v[28:31], v[204:207], v[240:243], v[28:31]
	v_mfma_f32_16x16x32_bf16 v[24:27], v[212:215], v[240:243], v[24:27]
	v_mfma_f32_16x16x32_bf16 v[12:15], v[204:207], v[244:247], v[12:15]
	v_mfma_f32_16x16x32_bf16 v[6:9], v[212:215], v[244:247], v[6:9]
	s_setprio 0
	s_barrier
	v_add_u32_e32 v4, s83, v159
	v_add_u32_e32 v10, s83, v173
	ds_read_b128 v[136:139], v4
	ds_read_b128 v[140:143], v10
	v_add_u32_e32 v4, s81, v159
	v_add_u32_e32 v10, s81, v173
	ds_read_b128 v[180:183], v4
	ds_read_b128 v[196:199], v10
	v_add_u32_e32 v4, s84, v159
	v_add_u32_e32 v10, s84, v173
	ds_read_b128 v[200:203], v4
	ds_read_b128 v[204:207], v10
	v_add_u32_e32 v4, s82, v159
	v_add_u32_e32 v10, s82, v173
	ds_read_b128 v[208:211], v4
	ds_read_b128 v[212:215], v10
	s_mov_b32 m0, s66
	v_lshl_add_u64 v[10:11], s[26:27], 0, v[144:145]
	ds_read_b128 v[216:219], v176 offset:32768
	ds_read_b128 v[220:223], v176 offset:34816
	ds_read_b128 v[224:227], v177 offset:32768
	ds_read_b128 v[228:231], v177 offset:34816
	ds_read_b128 v[232:235], v176 offset:36864
	ds_read_b128 v[236:239], v176 offset:38912
	ds_read_b128 v[240:243], v177 offset:36864
	ds_read_b128 v[244:247], v177 offset:38912
	global_load_lds_dwordx4 v[10:11], off
	v_lshl_add_u64 v[248:249], v[10:11], 0, s[18:19]
	s_mov_b32 m0, s67
	s_nop 0
	global_load_lds_dwordx4 v[248:249], off
	v_lshl_add_u64 v[248:249], v[10:11], 0, s[12:13]
	s_mov_b32 m0, s68
	v_lshl_add_u64 v[10:11], v[10:11], 0, s[20:21]
	global_load_lds_dwordx4 v[248:249], off
	s_mov_b32 m0, s69
	s_nop 0
	global_load_lds_dwordx4 v[10:11], off
	s_waitcnt vmcnt(8)
	s_waitcnt lgkmcnt(0)
	s_setprio 1
	s_barrier
	v_mfma_f32_16x16x32_bf16 v[132:135], v[136:139], v[216:219], v[132:135]
	v_mfma_f32_16x16x32_bf16 v[128:131], v[180:183], v[216:219], v[128:131]
	v_mfma_f32_16x16x32_bf16 v[116:119], v[136:139], v[220:223], v[116:119]
	v_mfma_f32_16x16x32_bf16 v[112:115], v[180:183], v[220:223], v[112:115]
	v_mfma_f32_16x16x32_bf16 v[100:103], v[136:139], v[232:235], v[100:103]
	v_mfma_f32_16x16x32_bf16 v[96:99], v[180:183], v[232:235], v[96:99]
	v_mfma_f32_16x16x32_bf16 v[84:87], v[136:139], v[236:239], v[84:87]
	v_mfma_f32_16x16x32_bf16 v[80:83], v[180:183], v[236:239], v[80:83]
	v_mfma_f32_16x16x32_bf16 v[132:135], v[140:143], v[224:227], v[132:135]
	v_mfma_f32_16x16x32_bf16 v[128:131], v[196:199], v[224:227], v[128:131]
	v_mfma_f32_16x16x32_bf16 v[116:119], v[140:143], v[228:231], v[116:119]
	v_mfma_f32_16x16x32_bf16 v[112:115], v[196:199], v[228:231], v[112:115]
	v_mfma_f32_16x16x32_bf16 v[100:103], v[140:143], v[240:243], v[100:103]
	v_mfma_f32_16x16x32_bf16 v[96:99], v[196:199], v[240:243], v[96:99]
	v_mfma_f32_16x16x32_bf16 v[84:87], v[140:143], v[244:247], v[84:87]
	v_mfma_f32_16x16x32_bf16 v[80:83], v[196:199], v[244:247], v[80:83]
	v_mfma_f32_16x16x32_bf16 v[124:127], v[200:203], v[216:219], v[124:127]
	v_mfma_f32_16x16x32_bf16 v[120:123], v[208:211], v[216:219], v[120:123]
	v_mfma_f32_16x16x32_bf16 v[108:111], v[200:203], v[220:223], v[108:111]
	v_mfma_f32_16x16x32_bf16 v[104:107], v[208:211], v[220:223], v[104:107]
	v_mfma_f32_16x16x32_bf16 v[92:95], v[200:203], v[232:235], v[92:95]
	v_mfma_f32_16x16x32_bf16 v[88:91], v[208:211], v[232:235], v[88:91]
	v_mfma_f32_16x16x32_bf16 v[76:79], v[200:203], v[236:239], v[76:79]
	v_mfma_f32_16x16x32_bf16 v[72:75], v[208:211], v[236:239], v[72:75]
	v_mfma_f32_16x16x32_bf16 v[124:127], v[204:207], v[224:227], v[124:127]
	v_mfma_f32_16x16x32_bf16 v[120:123], v[212:215], v[224:227], v[120:123]
	v_mfma_f32_16x16x32_bf16 v[108:111], v[204:207], v[228:231], v[108:111]
	v_mfma_f32_16x16x32_bf16 v[104:107], v[212:215], v[228:231], v[104:107]
	v_mfma_f32_16x16x32_bf16 v[92:95], v[204:207], v[240:243], v[92:95]
	v_mfma_f32_16x16x32_bf16 v[88:91], v[212:215], v[240:243], v[88:91]
	v_mfma_f32_16x16x32_bf16 v[76:79], v[204:207], v[244:247], v[76:79]
	v_mfma_f32_16x16x32_bf16 v[72:75], v[212:215], v[244:247], v[72:75]
	s_setprio 0
	s_barrier
	s_add_i32 s26, s83, s3
	v_lshl_add_u64 v[10:11], v[184:185], 0, s[24:25]
	s_mov_b32 m0, s26
	ds_read_b128 v[216:219], v176 offset:49152
	ds_read_b128 v[220:223], v176 offset:51200
	ds_read_b128 v[224:227], v177 offset:49152
	ds_read_b128 v[228:231], v177 offset:51200
	ds_read_b128 v[232:235], v176 offset:53248
	ds_read_b128 v[236:239], v176 offset:55296
	ds_read_b128 v[240:243], v177 offset:53248
	ds_read_b128 v[244:247], v177 offset:55296
	global_load_lds_dwordx4 v[10:11], off
	v_lshl_add_u64 v[10:11], v[184:185], 0, s[50:51]
	s_add_i32 m0, s26, 0x2000
	s_add_i32 s26, s84, s3
	global_load_lds_dwordx4 v[10:11], off
	v_lshl_add_u64 v[10:11], v[184:185], 0, s[52:53]
	s_mov_b32 m0, s26
	s_nop 0
	global_load_lds_dwordx4 v[10:11], off
	v_lshl_add_u64 v[10:11], v[184:185], 0, s[54:55]
	s_add_i32 m0, s26, 0x2000
	s_nop 0
	global_load_lds_dwordx4 v[10:11], off
	s_waitcnt vmcnt(4)
	s_waitcnt lgkmcnt(0)
	s_setprio 1
	s_barrier
	v_mfma_f32_16x16x32_bf16 v[68:71], v[136:139], v[216:219], v[68:71]
	v_mfma_f32_16x16x32_bf16 v[64:67], v[180:183], v[216:219], v[64:67]
	v_mfma_f32_16x16x32_bf16 v[52:55], v[136:139], v[220:223], v[52:55]
	v_mfma_f32_16x16x32_bf16 v[48:51], v[180:183], v[220:223], v[48:51]
	v_mfma_f32_16x16x32_bf16 v[36:39], v[136:139], v[232:235], v[36:39]
	v_mfma_f32_16x16x32_bf16 v[32:35], v[180:183], v[232:235], v[32:35]
	v_mfma_f32_16x16x32_bf16 v[20:23], v[136:139], v[236:239], v[20:23]
	v_mfma_f32_16x16x32_bf16 v[16:19], v[180:183], v[236:239], v[16:19]
	v_mfma_f32_16x16x32_bf16 v[68:71], v[140:143], v[224:227], v[68:71]
	v_mfma_f32_16x16x32_bf16 v[64:67], v[196:199], v[224:227], v[64:67]
	v_mfma_f32_16x16x32_bf16 v[52:55], v[140:143], v[228:231], v[52:55]
	v_mfma_f32_16x16x32_bf16 v[48:51], v[196:199], v[228:231], v[48:51]
	v_mfma_f32_16x16x32_bf16 v[36:39], v[140:143], v[240:243], v[36:39]
	v_mfma_f32_16x16x32_bf16 v[32:35], v[196:199], v[240:243], v[32:35]
	v_mfma_f32_16x16x32_bf16 v[20:23], v[140:143], v[244:247], v[20:23]
	v_mfma_f32_16x16x32_bf16 v[16:19], v[196:199], v[244:247], v[16:19]
	v_mfma_f32_16x16x32_bf16 v[60:63], v[200:203], v[216:219], v[60:63]
	v_mfma_f32_16x16x32_bf16 v[56:59], v[208:211], v[216:219], v[56:59]
	v_mfma_f32_16x16x32_bf16 v[44:47], v[200:203], v[220:223], v[44:47]
	v_mfma_f32_16x16x32_bf16 v[40:43], v[208:211], v[220:223], v[40:43]
	v_mfma_f32_16x16x32_bf16 v[28:31], v[200:203], v[232:235], v[28:31]
	v_mfma_f32_16x16x32_bf16 v[24:27], v[208:211], v[232:235], v[24:27]
	v_mfma_f32_16x16x32_bf16 v[10:13], v[200:203], v[236:239], v[12:15]
	v_mfma_f32_16x16x32_bf16 v[6:9], v[208:211], v[236:239], v[6:9]
	v_mfma_f32_16x16x32_bf16 v[60:63], v[204:207], v[224:227], v[60:63]
	v_mfma_f32_16x16x32_bf16 v[56:59], v[212:215], v[224:227], v[56:59]
	v_mfma_f32_16x16x32_bf16 v[44:47], v[204:207], v[228:231], v[44:47]
	v_mfma_f32_16x16x32_bf16 v[40:43], v[212:215], v[228:231], v[40:43]
	v_mfma_f32_16x16x32_bf16 v[28:31], v[204:207], v[240:243], v[28:31]
	v_mfma_f32_16x16x32_bf16 v[24:27], v[212:215], v[240:243], v[24:27]
	v_mfma_f32_16x16x32_bf16 v[12:15], v[204:207], v[244:247], v[10:13]
	v_mfma_f32_16x16x32_bf16 v[8:11], v[212:215], v[244:247], v[6:9]
	s_setprio 0
	s_barrier
	s_add_i32 s95, s95, 2
	s_add_u32 s64, s64, 0x100
	s_addc_u32 s65, s65, 0
	s_cmp_gt_u32 s95, 21
	s_cbranch_scc1 .LBB0_782

.LBB0_973:
	v_add_u32_e32 v133, s72, v163
	v_add_u32_e32 v140, s72, v164
	ds_read_b128 v[136:139], v133
	ds_read_b128 v[148:151], v140
	v_add_u32_e32 v133, s73, v163
	s_add_u32 s70, s28, s26
	v_add_u32_e32 v140, s73, v164
	s_waitcnt lgkmcnt(0)
	ds_read_b128 v[152:155], v133
	ds_read_b128 v[174:177], v140
	v_add_u32_e32 v133, s77, v163
	s_addc_u32 s71, s29, s27
	v_add_u32_e32 v140, s77, v164
	ds_read_b128 v[178:181], v133
	ds_read_b128 v[182:185], v140
	v_add_u32_e32 v133, s79, v163
	s_add_u32 s70, s70, 0x100
	v_add_u32_e32 v140, s79, v164
	ds_read_b128 v[196:199], v133
	ds_read_b128 v[200:203], v140
	s_addc_u32 s71, s71, 0
	s_add_u32 s86, s65, s26
	s_addc_u32 s87, s85, s27
	s_cmpk_eq_i32 s26, 0x700
	s_cselect_b32 s87, s61, s87
	s_cselect_b32 s86, s88, s86
	s_cselect_b32 s71, s54, s71
	s_cselect_b32 s70, s63, s70
	v_lshl_add_u64 v[140:141], v[134:135], 0, s[26:27]
	v_lshl_add_u64 v[160:161], v[140:141], 0, s[36:37]
	s_add_i32 m0, s5, 0x8000
	s_mov_b64 s[90:91], 0x20080
	ds_read_b128 v[204:207], v166
	ds_read_b128 v[208:211], v166 offset:2048
	ds_read_b128 v[212:215], v167
	ds_read_b128 v[216:219], v167 offset:2048
	ds_read_b128 v[220:223], v166 offset:4096
	ds_read_b128 v[224:227], v166 offset:6144
	ds_read_b128 v[228:231], v167 offset:4096
	ds_read_b128 v[232:235], v167 offset:6144
	global_load_lds_dwordx4 v[160:161], off
	v_lshl_add_u64 v[160:161], v[140:141], 0, s[90:91]
	s_add_i32 m0, s5, 0xa000
	s_mov_b64 s[90:91], 0x60080
	global_load_lds_dwordx4 v[160:161], off
	v_lshl_add_u64 v[160:161], v[140:141], 0, s[44:45]
	s_add_i32 m0, s5, 0xc000
	v_lshl_add_u64 v[140:141], v[140:141], 0, s[90:91]
	global_load_lds_dwordx4 v[160:161], off
	s_add_i32 m0, s5, 0xe000
	s_nop 0
	global_load_lds_dwordx4 v[140:141], off
	s_waitcnt vmcnt(8)
	s_waitcnt lgkmcnt(0)
	s_setprio 1
	s_barrier
	v_mfma_f32_16x16x32_bf16 v[8:11], v[136:139], v[204:207], v[8:11]
	v_mfma_f32_16x16x32_bf16 v[4:7], v[152:155], v[204:207], v[4:7]
	v_mfma_f32_16x16x32_bf16 v[12:15], v[136:139], v[208:211], v[12:15]
	v_mfma_f32_16x16x32_bf16 v[16:19], v[152:155], v[208:211], v[16:19]
	v_mfma_f32_16x16x32_bf16 v[44:47], v[136:139], v[220:223], v[44:47]
	v_mfma_f32_16x16x32_bf16 v[36:39], v[152:155], v[220:223], v[36:39]
	v_mfma_f32_16x16x32_bf16 v[20:23], v[136:139], v[224:227], v[20:23]
	v_mfma_f32_16x16x32_bf16 v[24:27], v[152:155], v[224:227], v[24:27]
	v_mfma_f32_16x16x32_bf16 v[8:11], v[148:151], v[212:215], v[8:11]
	v_mfma_f32_16x16x32_bf16 v[4:7], v[174:177], v[212:215], v[4:7]
	v_mfma_f32_16x16x32_bf16 v[12:15], v[148:151], v[216:219], v[12:15]
	v_mfma_f32_16x16x32_bf16 v[16:19], v[174:177], v[216:219], v[16:19]
	v_mfma_f32_16x16x32_bf16 v[44:47], v[148:151], v[228:231], v[44:47]
	v_mfma_f32_16x16x32_bf16 v[36:39], v[174:177], v[228:231], v[36:39]
	v_mfma_f32_16x16x32_bf16 v[20:23], v[148:151], v[232:235], v[20:23]
	v_mfma_f32_16x16x32_bf16 v[24:27], v[174:177], v[232:235], v[24:27]
	v_mfma_f32_16x16x32_bf16 v[32:35], v[178:181], v[204:207], v[32:35]
	v_mfma_f32_16x16x32_bf16 v[28:31], v[196:199], v[204:207], v[28:31]
	v_mfma_f32_16x16x32_bf16 v[40:43], v[178:181], v[208:211], v[40:43]
	v_mfma_f32_16x16x32_bf16 v[52:55], v[196:199], v[208:211], v[52:55]
	v_mfma_f32_16x16x32_bf16 v[48:51], v[178:181], v[220:223], v[48:51]
	v_mfma_f32_16x16x32_bf16 v[60:63], v[196:199], v[220:223], v[60:63]
	v_mfma_f32_16x16x32_bf16 v[56:59], v[178:181], v[224:227], v[56:59]
	v_mfma_f32_16x16x32_bf16 v[64:67], v[196:199], v[224:227], v[64:67]
	v_mfma_f32_16x16x32_bf16 v[32:35], v[182:185], v[212:215], v[32:35]
	v_mfma_f32_16x16x32_bf16 v[28:31], v[200:203], v[212:215], v[28:31]
	v_mfma_f32_16x16x32_bf16 v[40:43], v[182:185], v[216:219], v[40:43]
	v_mfma_f32_16x16x32_bf16 v[52:55], v[200:203], v[216:219], v[52:55]
	v_mfma_f32_16x16x32_bf16 v[48:51], v[182:185], v[228:231], v[48:51]
	v_mfma_f32_16x16x32_bf16 v[60:63], v[200:203], v[228:231], v[60:63]
	v_mfma_f32_16x16x32_bf16 v[56:59], v[182:185], v[232:235], v[56:59]
	v_mfma_f32_16x16x32_bf16 v[64:67], v[200:203], v[232:235], v[64:67]
	s_setprio 0
	s_barrier
	v_lshl_add_u64 v[140:141], s[86:87], 0, v[158:159]
	s_add_i32 s86, s72, s34
	s_mov_b32 m0, s86
	ds_read_b128 v[204:207], v166 offset:16384
	ds_read_b128 v[208:211], v166 offset:18432
	ds_read_b128 v[212:215], v167 offset:16384
	ds_read_b128 v[216:219], v167 offset:18432
	ds_read_b128 v[220:223], v166 offset:20480
	ds_read_b128 v[224:227], v166 offset:22528
	ds_read_b128 v[228:231], v167 offset:20480
	ds_read_b128 v[232:235], v167 offset:22528
	global_load_lds_dwordx4 v[140:141], off
	v_lshl_add_u64 v[160:161], v[140:141], 0, s[18:19]
	s_add_i32 m0, s86, 0x2000
	s_mov_b64 s[86:87], 0x10000
	global_load_lds_dwordx4 v[160:161], off
	v_lshl_add_u64 v[160:161], v[140:141], 0, s[86:87]
	s_add_i32 s86, s77, s34
	s_mov_b32 m0, s86
	s_nop 0
	global_load_lds_dwordx4 v[160:161], off
	v_lshl_add_u64 v[160:161], v[140:141], 0, s[20:21]
	s_add_i32 m0, s86, 0x2000
	s_nop 0
	global_load_lds_dwordx4 v[160:161], off
	s_waitcnt vmcnt(4)
	s_waitcnt lgkmcnt(0)
	s_setprio 1
	s_barrier
	v_mfma_f32_16x16x32_bf16 v[68:71], v[136:139], v[204:207], v[68:71]
	v_mfma_f32_16x16x32_bf16 v[72:75], v[152:155], v[204:207], v[72:75]
	v_mfma_f32_16x16x32_bf16 v[92:95], v[136:139], v[208:211], v[92:95]
	v_mfma_f32_16x16x32_bf16 v[84:87], v[152:155], v[208:211], v[84:87]
	v_mfma_f32_16x16x32_bf16 v[76:79], v[136:139], v[220:223], v[76:79]
	v_mfma_f32_16x16x32_bf16 v[80:83], v[152:155], v[220:223], v[80:83]
	v_mfma_f32_16x16x32_bf16 v[116:119], v[136:139], v[224:227], v[116:119]
	v_mfma_f32_16x16x32_bf16 v[108:111], v[152:155], v[224:227], v[108:111]
	v_mfma_f32_16x16x32_bf16 v[68:71], v[148:151], v[212:215], v[68:71]
	v_mfma_f32_16x16x32_bf16 v[72:75], v[174:177], v[212:215], v[72:75]
	v_mfma_f32_16x16x32_bf16 v[92:95], v[148:151], v[216:219], v[92:95]
	v_mfma_f32_16x16x32_bf16 v[84:87], v[174:177], v[216:219], v[84:87]
	v_mfma_f32_16x16x32_bf16 v[76:79], v[148:151], v[228:231], v[76:79]
	v_mfma_f32_16x16x32_bf16 v[80:83], v[174:177], v[228:231], v[80:83]
	v_mfma_f32_16x16x32_bf16 v[116:119], v[148:151], v[232:235], v[116:119]
	v_mfma_f32_16x16x32_bf16 v[108:111], v[174:177], v[232:235], v[108:111]
	v_mfma_f32_16x16x32_bf16 v[88:91], v[178:181], v[204:207], v[88:91]
	v_mfma_f32_16x16x32_bf16 v[100:103], v[196:199], v[204:207], v[100:103]
	v_mfma_f32_16x16x32_bf16 v[96:99], v[178:181], v[208:211], v[96:99]
	v_mfma_f32_16x16x32_bf16 v[104:107], v[196:199], v[208:211], v[104:107]
	v_mfma_f32_16x16x32_bf16 v[112:115], v[178:181], v[220:223], v[112:115]
	v_mfma_f32_16x16x32_bf16 v[124:127], v[196:199], v[220:223], v[124:127]
	v_mfma_f32_16x16x32_bf16 v[120:123], v[178:181], v[224:227], v[120:123]
	v_mfma_f32_16x16x32_bf16 v[128:131], v[196:199], v[224:227], v[128:131]
	v_mfma_f32_16x16x32_bf16 v[88:91], v[182:185], v[212:215], v[88:91]
	v_mfma_f32_16x16x32_bf16 v[100:103], v[200:203], v[212:215], v[100:103]
	v_mfma_f32_16x16x32_bf16 v[96:99], v[182:185], v[216:219], v[96:99]
	v_mfma_f32_16x16x32_bf16 v[104:107], v[200:203], v[216:219], v[104:107]
	v_mfma_f32_16x16x32_bf16 v[112:115], v[182:185], v[228:231], v[112:115]
	v_mfma_f32_16x16x32_bf16 v[124:127], v[200:203], v[228:231], v[124:127]
	v_mfma_f32_16x16x32_bf16 v[120:123], v[182:185], v[232:235], v[120:123]
	v_mfma_f32_16x16x32_bf16 v[128:131], v[200:203], v[232:235], v[128:131]
	s_setprio 0
	s_barrier
	v_add_u32_e32 v133, s82, v163
	v_add_u32_e32 v148, s82, v164
	ds_read_b128 v[136:139], v133
	ds_read_b128 v[148:151], v148
	v_add_u32_e32 v133, s80, v163
	v_add_u32_e32 v160, s80, v164
	ds_read_b128 v[152:155], v133
	ds_read_b128 v[174:177], v160
	v_add_u32_e32 v133, s83, v163
	v_add_u32_e32 v160, s83, v164
	ds_read_b128 v[178:181], v133
	ds_read_b128 v[182:185], v160
	v_add_u32_e32 v133, s81, v163
	v_add_u32_e32 v160, s81, v164
	ds_read_b128 v[196:199], v133
	ds_read_b128 v[200:203], v160
	s_mov_b32 m0, s5
	v_lshl_add_u64 v[160:161], s[70:71], 0, v[0:1]
	s_mov_b64 s[70:71], 0x20000
	ds_read_b128 v[204:207], v166 offset:32768
	ds_read_b128 v[208:211], v166 offset:34816
	ds_read_b128 v[212:215], v167 offset:32768
	ds_read_b128 v[216:219], v167 offset:34816
	ds_read_b128 v[220:223], v166 offset:36864
	ds_read_b128 v[224:227], v166 offset:38912
	ds_read_b128 v[228:231], v167 offset:36864
	ds_read_b128 v[232:235], v167 offset:38912
	global_load_lds_dwordx4 v[160:161], off
	v_lshl_add_u64 v[170:171], v[160:161], 0, s[70:71]
	s_mov_b32 m0, s17
	s_nop 0
	global_load_lds_dwordx4 v[170:171], off
	v_lshl_add_u64 v[170:171], v[160:161], 0, s[18:19]
	s_mov_b32 m0, s35
	v_lshl_add_u64 v[160:161], v[160:161], 0, s[22:23]
	global_load_lds_dwordx4 v[170:171], off
	s_mov_b32 m0, s38
	s_nop 0
	global_load_lds_dwordx4 v[160:161], off
	s_waitcnt vmcnt(8)
	s_waitcnt lgkmcnt(0)
	s_setprio 1
	s_barrier
	v_mfma_f32_16x16x32_bf16 v[8:11], v[136:139], v[204:207], v[8:11]
	v_mfma_f32_16x16x32_bf16 v[4:7], v[152:155], v[204:207], v[4:7]
	v_mfma_f32_16x16x32_bf16 v[12:15], v[136:139], v[208:211], v[12:15]
	v_mfma_f32_16x16x32_bf16 v[16:19], v[152:155], v[208:211], v[16:19]
	v_mfma_f32_16x16x32_bf16 v[44:47], v[136:139], v[220:223], v[44:47]
	v_mfma_f32_16x16x32_bf16 v[36:39], v[152:155], v[220:223], v[36:39]
	v_mfma_f32_16x16x32_bf16 v[20:23], v[136:139], v[224:227], v[20:23]
	v_mfma_f32_16x16x32_bf16 v[24:27], v[152:155], v[224:227], v[24:27]
	v_mfma_f32_16x16x32_bf16 v[8:11], v[148:151], v[212:215], v[8:11]
	v_mfma_f32_16x16x32_bf16 v[4:7], v[174:177], v[212:215], v[4:7]
	v_mfma_f32_16x16x32_bf16 v[12:15], v[148:151], v[216:219], v[12:15]
	v_mfma_f32_16x16x32_bf16 v[16:19], v[174:177], v[216:219], v[16:19]
	v_mfma_f32_16x16x32_bf16 v[44:47], v[148:151], v[228:231], v[44:47]
	v_mfma_f32_16x16x32_bf16 v[36:39], v[174:177], v[228:231], v[36:39]
	v_mfma_f32_16x16x32_bf16 v[20:23], v[148:151], v[232:235], v[20:23]
	v_mfma_f32_16x16x32_bf16 v[24:27], v[174:177], v[232:235], v[24:27]
	v_mfma_f32_16x16x32_bf16 v[32:35], v[178:181], v[204:207], v[32:35]
	v_mfma_f32_16x16x32_bf16 v[28:31], v[196:199], v[204:207], v[28:31]
	v_mfma_f32_16x16x32_bf16 v[40:43], v[178:181], v[208:211], v[40:43]
	v_mfma_f32_16x16x32_bf16 v[52:55], v[196:199], v[208:211], v[52:55]
	v_mfma_f32_16x16x32_bf16 v[48:51], v[178:181], v[220:223], v[48:51]
	v_mfma_f32_16x16x32_bf16 v[60:63], v[196:199], v[220:223], v[60:63]
	v_mfma_f32_16x16x32_bf16 v[56:59], v[178:181], v[224:227], v[56:59]
	v_mfma_f32_16x16x32_bf16 v[64:67], v[196:199], v[224:227], v[64:67]
	v_mfma_f32_16x16x32_bf16 v[32:35], v[182:185], v[212:215], v[32:35]
	v_mfma_f32_16x16x32_bf16 v[28:31], v[200:203], v[212:215], v[28:31]
	v_mfma_f32_16x16x32_bf16 v[40:43], v[182:185], v[216:219], v[40:43]
	v_mfma_f32_16x16x32_bf16 v[52:55], v[200:203], v[216:219], v[52:55]
	v_mfma_f32_16x16x32_bf16 v[48:51], v[182:185], v[228:231], v[48:51]
	v_mfma_f32_16x16x32_bf16 v[60:63], v[200:203], v[228:231], v[60:63]
	v_mfma_f32_16x16x32_bf16 v[56:59], v[182:185], v[232:235], v[56:59]
	v_mfma_f32_16x16x32_bf16 v[64:67], v[200:203], v[232:235], v[64:67]
	s_setprio 0
	s_barrier
	s_add_i32 s70, s82, s34
	v_lshl_add_u64 v[160:161], v[140:141], 0, s[36:37]
	s_mov_b32 m0, s70
	ds_read_b128 v[204:207], v166 offset:49152
	ds_read_b128 v[208:211], v166 offset:51200
	ds_read_b128 v[212:215], v167 offset:49152
	ds_read_b128 v[216:219], v167 offset:51200
	ds_read_b128 v[220:223], v166 offset:53248
	ds_read_b128 v[224:227], v166 offset:55296
	ds_read_b128 v[228:231], v167 offset:53248
	ds_read_b128 v[232:235], v167 offset:55296
	global_load_lds_dwordx4 v[160:161], off
	v_lshl_add_u64 v[160:161], v[140:141], 0, s[44:45]
	s_add_i32 m0, s70, 0x2000
	s_add_i32 s70, s83, s34
	global_load_lds_dwordx4 v[160:161], off
	v_lshl_add_u64 v[160:161], v[140:141], 0, s[46:47]
	s_mov_b32 m0, s70
	v_lshl_add_u64 v[140:141], v[140:141], 0, s[50:51]
	global_load_lds_dwordx4 v[160:161], off
	s_add_i32 m0, s70, 0x2000
	s_nop 0
	global_load_lds_dwordx4 v[140:141], off
	s_waitcnt vmcnt(4)
	s_waitcnt lgkmcnt(0)
	s_setprio 1
	s_barrier
	v_mfma_f32_16x16x32_bf16 v[68:71], v[136:139], v[204:207], v[68:71]
	v_mfma_f32_16x16x32_bf16 v[72:75], v[152:155], v[204:207], v[72:75]
	v_mfma_f32_16x16x32_bf16 v[92:95], v[136:139], v[208:211], v[92:95]
	v_mfma_f32_16x16x32_bf16 v[84:87], v[152:155], v[208:211], v[84:87]
	v_mfma_f32_16x16x32_bf16 v[76:79], v[136:139], v[220:223], v[76:79]
	v_mfma_f32_16x16x32_bf16 v[80:83], v[152:155], v[220:223], v[80:83]
	v_mfma_f32_16x16x32_bf16 v[116:119], v[136:139], v[224:227], v[116:119]
	v_mfma_f32_16x16x32_bf16 v[108:111], v[152:155], v[224:227], v[108:111]
	v_mfma_f32_16x16x32_bf16 v[68:71], v[148:151], v[212:215], v[68:71]
	v_mfma_f32_16x16x32_bf16 v[72:75], v[174:177], v[212:215], v[72:75]
	v_mfma_f32_16x16x32_bf16 v[92:95], v[148:151], v[216:219], v[92:95]
	v_mfma_f32_16x16x32_bf16 v[84:87], v[174:177], v[216:219], v[84:87]
	v_mfma_f32_16x16x32_bf16 v[76:79], v[148:151], v[228:231], v[76:79]
	v_mfma_f32_16x16x32_bf16 v[80:83], v[174:177], v[228:231], v[80:83]
	v_mfma_f32_16x16x32_bf16 v[116:119], v[148:151], v[232:235], v[116:119]
	v_mfma_f32_16x16x32_bf16 v[108:111], v[174:177], v[232:235], v[108:111]
	v_mfma_f32_16x16x32_bf16 v[88:91], v[178:181], v[204:207], v[88:91]
	v_mfma_f32_16x16x32_bf16 v[100:103], v[196:199], v[204:207], v[100:103]
	v_mfma_f32_16x16x32_bf16 v[96:99], v[178:181], v[208:211], v[96:99]
	v_mfma_f32_16x16x32_bf16 v[104:107], v[196:199], v[208:211], v[104:107]
	v_mfma_f32_16x16x32_bf16 v[112:115], v[178:181], v[220:223], v[112:115]
	v_mfma_f32_16x16x32_bf16 v[124:127], v[196:199], v[220:223], v[124:127]
	v_mfma_f32_16x16x32_bf16 v[120:123], v[178:181], v[224:227], v[120:123]
	v_mfma_f32_16x16x32_bf16 v[128:131], v[196:199], v[224:227], v[128:131]
	v_mfma_f32_16x16x32_bf16 v[88:91], v[182:185], v[212:215], v[88:91]
	v_mfma_f32_16x16x32_bf16 v[100:103], v[200:203], v[212:215], v[100:103]
	v_mfma_f32_16x16x32_bf16 v[96:99], v[182:185], v[216:219], v[96:99]
	v_mfma_f32_16x16x32_bf16 v[104:107], v[200:203], v[216:219], v[104:107]
	v_mfma_f32_16x16x32_bf16 v[112:115], v[182:185], v[228:231], v[112:115]
	v_mfma_f32_16x16x32_bf16 v[124:127], v[200:203], v[228:231], v[124:127]
	v_mfma_f32_16x16x32_bf16 v[120:123], v[182:185], v[232:235], v[120:123]
	v_mfma_f32_16x16x32_bf16 v[128:131], v[200:203], v[232:235], v[128:131]
	s_setprio 0
	s_barrier
	s_add_i32 s89, s89, 2
	s_add_u32 s26, s26, 0x100
	s_addc_u32 s27, s27, 0
	s_cmp_gt_u32 s89, 13
	s_cbranch_scc0 .LBB0_973
	s_and_b64 vcc, exec, s[52:53]
	s_cbranch_vccz .LBB0_976
	s_barrier

.LBB0_1135:
	ds_read_b128 v[168:171], v145
	ds_read_b128 v[174:177], v146
	ds_read_b128 v[178:181], v147
	ds_read_b128 v[182:185], v148
	ds_read_b128 v[194:197], v149
	ds_read_b128 v[198:201], v150
	ds_read_b128 v[202:205], v151
	ds_read_b128 v[206:209], v152
	s_add_u32 s70, s26, s68
	s_addc_u32 s71, s27, s69
	s_add_u32 s70, s70, 0x100
	s_addc_u32 s71, s71, 0
	s_add_u32 s84, s81, s68
	s_addc_u32 s85, s82, s69
	s_cmpk_eq_i32 s68, 0x700
	s_cselect_b32 s85, s59, s85
	s_cselect_b32 s84, s80, s84
	s_cselect_b32 s71, s57, s71
	s_cselect_b32 s70, s79, s70
	v_lshl_add_u64 v[140:141], v[138:139], 0, s[68:69]
	v_lshl_add_u64 v[242:243], v[140:141], 0, s[22:23]
	s_add_i32 m0, s34, 0x8000
	s_mov_b64 s[86:87], 0x20080
	ds_read_b128 v[210:213], v153
	ds_read_b128 v[214:217], v153 offset:2048
	ds_read_b128 v[218:221], v154
	ds_read_b128 v[222:225], v154 offset:2048
	ds_read_b128 v[226:229], v153 offset:4096
	ds_read_b128 v[230:233], v153 offset:6144
	ds_read_b128 v[234:237], v154 offset:4096
	ds_read_b128 v[238:241], v154 offset:6144
	global_load_lds_dwordx4 v[242:243], off
	v_lshl_add_u64 v[242:243], v[140:141], 0, s[86:87]
	s_add_i32 m0, s34, 0xa000
	s_mov_b64 s[86:87], 0x60080
	global_load_lds_dwordx4 v[242:243], off
	v_lshl_add_u64 v[242:243], v[140:141], 0, s[24:25]
	s_add_i32 m0, s34, 0xc000
	v_lshl_add_u64 v[140:141], v[140:141], 0, s[86:87]
	global_load_lds_dwordx4 v[242:243], off
	s_add_i32 m0, s34, 0xe000
	s_nop 0
	global_load_lds_dwordx4 v[140:141], off
	s_waitcnt vmcnt(8)
	s_waitcnt lgkmcnt(0)
	s_setprio 1
	s_barrier
	v_mfma_f32_16x16x32_bf16 v[128:131], v[168:171], v[210:213], v[128:131]
	v_mfma_f32_16x16x32_bf16 v[124:127], v[178:181], v[210:213], v[124:127]
	v_mfma_f32_16x16x32_bf16 v[112:115], v[168:171], v[214:217], v[112:115]
	v_mfma_f32_16x16x32_bf16 v[108:111], v[178:181], v[214:217], v[108:111]
	v_mfma_f32_16x16x32_bf16 v[96:99], v[168:171], v[226:229], v[96:99]
	v_mfma_f32_16x16x32_bf16 v[92:95], v[178:181], v[226:229], v[92:95]
	v_mfma_f32_16x16x32_bf16 v[80:83], v[168:171], v[230:233], v[80:83]
	v_mfma_f32_16x16x32_bf16 v[76:79], v[178:181], v[230:233], v[76:79]
	v_mfma_f32_16x16x32_bf16 v[128:131], v[174:177], v[218:221], v[128:131]
	v_mfma_f32_16x16x32_bf16 v[124:127], v[182:185], v[218:221], v[124:127]
	v_mfma_f32_16x16x32_bf16 v[112:115], v[174:177], v[222:225], v[112:115]
	v_mfma_f32_16x16x32_bf16 v[108:111], v[182:185], v[222:225], v[108:111]
	v_mfma_f32_16x16x32_bf16 v[96:99], v[174:177], v[234:237], v[96:99]
	v_mfma_f32_16x16x32_bf16 v[92:95], v[182:185], v[234:237], v[92:95]
	v_mfma_f32_16x16x32_bf16 v[80:83], v[174:177], v[238:241], v[80:83]
	v_mfma_f32_16x16x32_bf16 v[76:79], v[182:185], v[238:241], v[76:79]
	v_mfma_f32_16x16x32_bf16 v[120:123], v[194:197], v[210:213], v[120:123]
	v_mfma_f32_16x16x32_bf16 v[116:119], v[202:205], v[210:213], v[116:119]
	v_mfma_f32_16x16x32_bf16 v[104:107], v[194:197], v[214:217], v[104:107]
	v_mfma_f32_16x16x32_bf16 v[100:103], v[202:205], v[214:217], v[100:103]
	v_mfma_f32_16x16x32_bf16 v[88:91], v[194:197], v[226:229], v[88:91]
	v_mfma_f32_16x16x32_bf16 v[84:87], v[202:205], v[226:229], v[84:87]
	v_mfma_f32_16x16x32_bf16 v[72:75], v[194:197], v[230:233], v[72:75]
	v_mfma_f32_16x16x32_bf16 v[68:71], v[202:205], v[230:233], v[68:71]
	v_mfma_f32_16x16x32_bf16 v[120:123], v[198:201], v[218:221], v[120:123]
	v_mfma_f32_16x16x32_bf16 v[116:119], v[206:209], v[218:221], v[116:119]
	v_mfma_f32_16x16x32_bf16 v[104:107], v[198:201], v[222:225], v[104:107]
	v_mfma_f32_16x16x32_bf16 v[100:103], v[206:209], v[222:225], v[100:103]
	v_mfma_f32_16x16x32_bf16 v[88:91], v[198:201], v[234:237], v[88:91]
	v_mfma_f32_16x16x32_bf16 v[84:87], v[206:209], v[234:237], v[84:87]
	v_mfma_f32_16x16x32_bf16 v[72:75], v[198:201], v[238:241], v[72:75]
	v_mfma_f32_16x16x32_bf16 v[68:71], v[206:209], v[238:241], v[68:71]
	s_setprio 0
	s_barrier
	v_lshl_add_u64 v[140:141], s[84:85], 0, v[158:159]
	s_add_i32 s84, s67, s3
	s_mov_b32 m0, s84
	ds_read_b128 v[210:213], v153 offset:16384
	ds_read_b128 v[214:217], v153 offset:18432
	ds_read_b128 v[218:221], v154 offset:16384
	ds_read_b128 v[222:225], v154 offset:18432
	ds_read_b128 v[226:229], v153 offset:20480
	ds_read_b128 v[230:233], v153 offset:22528
	ds_read_b128 v[234:237], v154 offset:20480
	ds_read_b128 v[238:241], v154 offset:22528
	global_load_lds_dwordx4 v[140:141], off
	v_lshl_add_u64 v[242:243], v[140:141], 0, s[0:1]
	s_add_i32 m0, s84, 0x2000
	s_add_i32 s84, s72, s3
	global_load_lds_dwordx4 v[242:243], off
	v_lshl_add_u64 v[242:243], v[140:141], 0, s[12:13]
	s_mov_b32 m0, s84
	s_nop 0
	global_load_lds_dwordx4 v[242:243], off
	v_lshl_add_u64 v[242:243], v[140:141], 0, s[14:15]
	s_add_i32 m0, s84, 0x2000
	s_nop 0
	global_load_lds_dwordx4 v[242:243], off
	s_waitcnt vmcnt(4)
	s_waitcnt lgkmcnt(0)
	s_setprio 1
	s_barrier
	v_mfma_f32_16x16x32_bf16 v[64:67], v[168:171], v[210:213], v[64:67]
	v_mfma_f32_16x16x32_bf16 v[60:63], v[178:181], v[210:213], v[60:63]
	v_mfma_f32_16x16x32_bf16 v[48:51], v[168:171], v[214:217], v[48:51]
	v_mfma_f32_16x16x32_bf16 v[44:47], v[178:181], v[214:217], v[44:47]
	v_mfma_f32_16x16x32_bf16 v[32:35], v[168:171], v[226:229], v[32:35]
	v_mfma_f32_16x16x32_bf16 v[28:31], v[178:181], v[226:229], v[28:31]
	v_mfma_f32_16x16x32_bf16 v[16:19], v[168:171], v[230:233], v[16:19]
	v_mfma_f32_16x16x32_bf16 v[12:15], v[178:181], v[230:233], v[12:15]
	v_mfma_f32_16x16x32_bf16 v[64:67], v[174:177], v[218:221], v[64:67]
	v_mfma_f32_16x16x32_bf16 v[60:63], v[182:185], v[218:221], v[60:63]
	v_mfma_f32_16x16x32_bf16 v[48:51], v[174:177], v[222:225], v[48:51]
	v_mfma_f32_16x16x32_bf16 v[44:47], v[182:185], v[222:225], v[44:47]
	v_mfma_f32_16x16x32_bf16 v[32:35], v[174:177], v[234:237], v[32:35]
	v_mfma_f32_16x16x32_bf16 v[28:31], v[182:185], v[234:237], v[28:31]
	v_mfma_f32_16x16x32_bf16 v[16:19], v[174:177], v[238:241], v[16:19]
	v_mfma_f32_16x16x32_bf16 v[12:15], v[182:185], v[238:241], v[12:15]
	v_mfma_f32_16x16x32_bf16 v[56:59], v[194:197], v[210:213], v[56:59]
	v_mfma_f32_16x16x32_bf16 v[52:55], v[202:205], v[210:213], v[52:55]
	v_mfma_f32_16x16x32_bf16 v[40:43], v[194:197], v[214:217], v[40:43]
	v_mfma_f32_16x16x32_bf16 v[36:39], v[202:205], v[214:217], v[36:39]
	v_mfma_f32_16x16x32_bf16 v[24:27], v[194:197], v[226:229], v[24:27]
	v_mfma_f32_16x16x32_bf16 v[20:23], v[202:205], v[226:229], v[20:23]
	v_mfma_f32_16x16x32_bf16 v[8:11], v[194:197], v[230:233], v[8:11]
	v_mfma_f32_16x16x32_bf16 v[4:7], v[202:205], v[230:233], v[4:7]
	v_mfma_f32_16x16x32_bf16 v[56:59], v[198:201], v[218:221], v[56:59]
	v_mfma_f32_16x16x32_bf16 v[52:55], v[206:209], v[218:221], v[52:55]
	v_mfma_f32_16x16x32_bf16 v[40:43], v[198:201], v[222:225], v[40:43]
	v_mfma_f32_16x16x32_bf16 v[36:39], v[206:209], v[222:225], v[36:39]
	v_mfma_f32_16x16x32_bf16 v[24:27], v[198:201], v[234:237], v[24:27]
	v_mfma_f32_16x16x32_bf16 v[20:23], v[206:209], v[234:237], v[20:23]
	v_mfma_f32_16x16x32_bf16 v[8:11], v[198:201], v[238:241], v[8:11]
	v_mfma_f32_16x16x32_bf16 v[4:7], v[206:209], v[238:241], v[4:7]
	s_setprio 0
	s_barrier
	ds_read_b128 v[168:171], v163
	ds_read_b128 v[174:177], v164
	ds_read_b128 v[178:181], v155
	ds_read_b128 v[182:185], v160
	ds_read_b128 v[194:197], v165
	ds_read_b128 v[198:201], v166
	ds_read_b128 v[202:205], v161
	ds_read_b128 v[206:209], v162
	s_mov_b32 m0, s34
	v_lshl_add_u64 v[242:243], s[70:71], 0, v[0:1]
	ds_read_b128 v[210:213], v153 offset:32768
	ds_read_b128 v[214:217], v153 offset:34816
	ds_read_b128 v[218:221], v154 offset:32768
	ds_read_b128 v[222:225], v154 offset:34816
	ds_read_b128 v[226:229], v153 offset:36864
	ds_read_b128 v[230:233], v153 offset:38912
	ds_read_b128 v[234:237], v154 offset:36864
	ds_read_b128 v[238:241], v154 offset:38912
	global_load_lds_dwordx4 v[242:243], off
	v_lshl_add_u64 v[244:245], v[242:243], 0, s[16:17]
	s_mov_b32 m0, s35
	s_nop 0
	global_load_lds_dwordx4 v[244:245], off
	v_lshl_add_u64 v[244:245], v[242:243], 0, s[0:1]
	s_mov_b32 m0, s38
	v_lshl_add_u64 v[242:243], v[242:243], 0, s[18:19]
	global_load_lds_dwordx4 v[244:245], off
	s_mov_b32 m0, s39
	s_nop 0
	global_load_lds_dwordx4 v[242:243], off
	s_waitcnt vmcnt(8)
	s_waitcnt lgkmcnt(0)
	s_setprio 1
	s_barrier
	v_mfma_f32_16x16x32_bf16 v[128:131], v[168:171], v[210:213], v[128:131]
	v_mfma_f32_16x16x32_bf16 v[124:127], v[178:181], v[210:213], v[124:127]
	v_mfma_f32_16x16x32_bf16 v[112:115], v[168:171], v[214:217], v[112:115]
	v_mfma_f32_16x16x32_bf16 v[108:111], v[178:181], v[214:217], v[108:111]
	v_mfma_f32_16x16x32_bf16 v[96:99], v[168:171], v[226:229], v[96:99]
	v_mfma_f32_16x16x32_bf16 v[92:95], v[178:181], v[226:229], v[92:95]
	v_mfma_f32_16x16x32_bf16 v[80:83], v[168:171], v[230:233], v[80:83]
	v_mfma_f32_16x16x32_bf16 v[76:79], v[178:181], v[230:233], v[76:79]
	v_mfma_f32_16x16x32_bf16 v[128:131], v[174:177], v[218:221], v[128:131]
	v_mfma_f32_16x16x32_bf16 v[124:127], v[182:185], v[218:221], v[124:127]
	v_mfma_f32_16x16x32_bf16 v[112:115], v[174:177], v[222:225], v[112:115]
	v_mfma_f32_16x16x32_bf16 v[108:111], v[182:185], v[222:225], v[108:111]
	v_mfma_f32_16x16x32_bf16 v[96:99], v[174:177], v[234:237], v[96:99]
	v_mfma_f32_16x16x32_bf16 v[92:95], v[182:185], v[234:237], v[92:95]
	v_mfma_f32_16x16x32_bf16 v[80:83], v[174:177], v[238:241], v[80:83]
	v_mfma_f32_16x16x32_bf16 v[76:79], v[182:185], v[238:241], v[76:79]
	v_mfma_f32_16x16x32_bf16 v[120:123], v[194:197], v[210:213], v[120:123]
	v_mfma_f32_16x16x32_bf16 v[116:119], v[202:205], v[210:213], v[116:119]
	v_mfma_f32_16x16x32_bf16 v[104:107], v[194:197], v[214:217], v[104:107]
	v_mfma_f32_16x16x32_bf16 v[100:103], v[202:205], v[214:217], v[100:103]
	v_mfma_f32_16x16x32_bf16 v[88:91], v[194:197], v[226:229], v[88:91]
	v_mfma_f32_16x16x32_bf16 v[84:87], v[202:205], v[226:229], v[84:87]
	v_mfma_f32_16x16x32_bf16 v[72:75], v[194:197], v[230:233], v[72:75]
	v_mfma_f32_16x16x32_bf16 v[68:71], v[202:205], v[230:233], v[68:71]
	v_mfma_f32_16x16x32_bf16 v[120:123], v[198:201], v[218:221], v[120:123]
	v_mfma_f32_16x16x32_bf16 v[116:119], v[206:209], v[218:221], v[116:119]
	v_mfma_f32_16x16x32_bf16 v[104:107], v[198:201], v[222:225], v[104:107]
	v_mfma_f32_16x16x32_bf16 v[100:103], v[206:209], v[222:225], v[100:103]
	v_mfma_f32_16x16x32_bf16 v[88:91], v[198:201], v[234:237], v[88:91]
	v_mfma_f32_16x16x32_bf16 v[84:87], v[206:209], v[234:237], v[84:87]
	v_mfma_f32_16x16x32_bf16 v[72:75], v[198:201], v[238:241], v[72:75]
	v_mfma_f32_16x16x32_bf16 v[68:71], v[206:209], v[238:241], v[68:71]
	s_setprio 0
	s_barrier
	s_add_i32 s70, s73, s3
	v_lshl_add_u64 v[242:243], v[140:141], 0, s[22:23]
	s_mov_b32 m0, s70
	ds_read_b128 v[210:213], v153 offset:49152
	ds_read_b128 v[214:217], v153 offset:51200
	ds_read_b128 v[218:221], v154 offset:49152
	ds_read_b128 v[222:225], v154 offset:51200
	ds_read_b128 v[226:229], v153 offset:53248
	ds_read_b128 v[230:233], v153 offset:55296
	ds_read_b128 v[234:237], v154 offset:53248
	ds_read_b128 v[238:241], v154 offset:55296
	global_load_lds_dwordx4 v[242:243], off
	v_lshl_add_u64 v[242:243], v[140:141], 0, s[24:25]
	s_add_i32 m0, s70, 0x2000
	s_add_i32 s70, s77, s3
	global_load_lds_dwordx4 v[242:243], off
	v_lshl_add_u64 v[242:243], v[140:141], 0, s[28:29]
	s_mov_b32 m0, s70
	v_lshl_add_u64 v[140:141], v[140:141], 0, s[36:37]
	global_load_lds_dwordx4 v[242:243], off
	s_add_i32 m0, s70, 0x2000
	s_nop 0
	global_load_lds_dwordx4 v[140:141], off
	s_waitcnt vmcnt(4)
	s_waitcnt lgkmcnt(0)
	s_setprio 1
	s_barrier
	v_mfma_f32_16x16x32_bf16 v[64:67], v[168:171], v[210:213], v[64:67]
	v_mfma_f32_16x16x32_bf16 v[60:63], v[178:181], v[210:213], v[60:63]
	v_mfma_f32_16x16x32_bf16 v[48:51], v[168:171], v[214:217], v[48:51]
	v_mfma_f32_16x16x32_bf16 v[44:47], v[178:181], v[214:217], v[44:47]
	v_mfma_f32_16x16x32_bf16 v[32:35], v[168:171], v[226:229], v[32:35]
	v_mfma_f32_16x16x32_bf16 v[28:31], v[178:181], v[226:229], v[28:31]
	v_mfma_f32_16x16x32_bf16 v[16:19], v[168:171], v[230:233], v[16:19]
	v_mfma_f32_16x16x32_bf16 v[12:15], v[178:181], v[230:233], v[12:15]
	v_mfma_f32_16x16x32_bf16 v[64:67], v[174:177], v[218:221], v[64:67]
	v_mfma_f32_16x16x32_bf16 v[60:63], v[182:185], v[218:221], v[60:63]
	v_mfma_f32_16x16x32_bf16 v[48:51], v[174:177], v[222:225], v[48:51]
	v_mfma_f32_16x16x32_bf16 v[44:47], v[182:185], v[222:225], v[44:47]
	v_mfma_f32_16x16x32_bf16 v[32:35], v[174:177], v[234:237], v[32:35]
	v_mfma_f32_16x16x32_bf16 v[28:31], v[182:185], v[234:237], v[28:31]
	v_mfma_f32_16x16x32_bf16 v[16:19], v[174:177], v[238:241], v[16:19]
	v_mfma_f32_16x16x32_bf16 v[12:15], v[182:185], v[238:241], v[12:15]
	v_mfma_f32_16x16x32_bf16 v[56:59], v[194:197], v[210:213], v[56:59]
	v_mfma_f32_16x16x32_bf16 v[52:55], v[202:205], v[210:213], v[52:55]
	v_mfma_f32_16x16x32_bf16 v[40:43], v[194:197], v[214:217], v[40:43]
	v_mfma_f32_16x16x32_bf16 v[36:39], v[202:205], v[214:217], v[36:39]
	v_mfma_f32_16x16x32_bf16 v[24:27], v[194:197], v[226:229], v[24:27]
	v_mfma_f32_16x16x32_bf16 v[20:23], v[202:205], v[226:229], v[20:23]
	v_mfma_f32_16x16x32_bf16 v[8:11], v[194:197], v[230:233], v[8:11]
	v_mfma_f32_16x16x32_bf16 v[4:7], v[202:205], v[230:233], v[4:7]
	v_mfma_f32_16x16x32_bf16 v[56:59], v[198:201], v[218:221], v[56:59]
	v_mfma_f32_16x16x32_bf16 v[52:55], v[206:209], v[218:221], v[52:55]
	v_mfma_f32_16x16x32_bf16 v[40:43], v[198:201], v[222:225], v[40:43]
	v_mfma_f32_16x16x32_bf16 v[36:39], v[206:209], v[222:225], v[36:39]
	v_mfma_f32_16x16x32_bf16 v[24:27], v[198:201], v[234:237], v[24:27]
	v_mfma_f32_16x16x32_bf16 v[20:23], v[206:209], v[234:237], v[20:23]
	v_mfma_f32_16x16x32_bf16 v[8:11], v[198:201], v[238:241], v[8:11]
	v_mfma_f32_16x16x32_bf16 v[4:7], v[206:209], v[238:241], v[4:7]
	s_setprio 0
	s_barrier
	s_add_i32 s83, s83, 2
	s_add_u32 s68, s68, 0x100
	s_addc_u32 s69, s69, 0
	s_cmp_gt_u32 s83, 13
	s_cbranch_scc0 .LBB0_1135
	s_and_b64 vcc, exec, s[40:41]
	s_cbranch_vccz .LBB0_1138
	s_barrier

.LBB0_1371:
	v_add_u32_e32 v147, s64, v143
	v_add_u32_e32 v152, s64, v144
	ds_read_b128 v[148:151], v147
	ds_read_b128 v[152:155], v152
	v_add_u32_e32 v147, s65, v143
	v_add_u32_e32 v162, s65, v144
	s_add_u32 s58, s18, s56
	ds_read_b128 v[158:161], v147
	ds_read_b128 v[162:165], v162
	v_add_u32_e32 v147, s66, v143
	s_addc_u32 s59, s19, s57
	v_add_u32_e32 v166, s66, v144
	ds_read_b128 v[170:173], v147
	ds_read_b128 v[174:177], v166
	v_add_u32_e32 v147, s67, v143
	s_add_u32 s58, s58, 0x100
	v_add_u32_e32 v166, s67, v144
	ds_read_b128 v[178:181], v147
	ds_read_b128 v[182:185], v166
	s_addc_u32 s59, s59, 0
	s_add_u32 s78, s53, s56
	s_addc_u32 s79, s72, s57
	s_cmpk_eq_i32 s56, 0x1f00
	s_cselect_b32 s79, s49, s79
	s_cselect_b32 s78, s76, s78
	s_cselect_b32 s59, s51, s59
	s_cselect_b32 s58, s73, s58
	v_lshl_add_u64 v[166:167], v[140:141], 0, s[56:57]
	v_lshl_add_u64 v[218:219], v[166:167], 0, s[24:25]
	s_add_i32 m0, s35, 0x8000
	ds_read_b128 v[186:189], v145
	ds_read_b128 v[190:193], v145 offset:2048
	ds_read_b128 v[194:197], v146
	ds_read_b128 v[198:201], v146 offset:2048
	ds_read_b128 v[202:205], v145 offset:4096
	ds_read_b128 v[206:209], v145 offset:6144
	ds_read_b128 v[210:213], v146 offset:4096
	ds_read_b128 v[214:217], v146 offset:6144
	global_load_lds_dwordx4 v[218:219], off
	v_lshl_add_u64 v[218:219], v[166:167], 0, s[44:45]
	s_add_i32 m0, s35, 0xa000
	s_nop 0
	global_load_lds_dwordx4 v[218:219], off
	v_lshl_add_u64 v[218:219], v[166:167], 0, s[28:29]
	s_add_i32 m0, s35, 0xc000
	v_lshl_add_u64 v[166:167], v[166:167], 0, s[46:47]
	global_load_lds_dwordx4 v[218:219], off
	s_add_i32 m0, s35, 0xe000
	s_nop 0
	global_load_lds_dwordx4 v[166:167], off
	s_waitcnt vmcnt(8)
	s_waitcnt lgkmcnt(0)
	s_setprio 1
	s_barrier
	v_mfma_f32_16x16x32_bf16 v[128:131], v[148:151], v[186:189], v[128:131]
	v_mfma_f32_16x16x32_bf16 v[124:127], v[158:161], v[186:189], v[124:127]
	v_mfma_f32_16x16x32_bf16 v[112:115], v[148:151], v[190:193], v[112:115]
	v_mfma_f32_16x16x32_bf16 v[108:111], v[158:161], v[190:193], v[108:111]
	v_mfma_f32_16x16x32_bf16 v[96:99], v[148:151], v[202:205], v[96:99]
	v_mfma_f32_16x16x32_bf16 v[92:95], v[158:161], v[202:205], v[92:95]
	v_mfma_f32_16x16x32_bf16 v[80:83], v[148:151], v[206:209], v[80:83]
	v_mfma_f32_16x16x32_bf16 v[76:79], v[158:161], v[206:209], v[76:79]
	v_mfma_f32_16x16x32_bf16 v[128:131], v[152:155], v[194:197], v[128:131]
	v_mfma_f32_16x16x32_bf16 v[124:127], v[162:165], v[194:197], v[124:127]
	v_mfma_f32_16x16x32_bf16 v[112:115], v[152:155], v[198:201], v[112:115]
	v_mfma_f32_16x16x32_bf16 v[108:111], v[162:165], v[198:201], v[108:111]
	v_mfma_f32_16x16x32_bf16 v[96:99], v[152:155], v[210:213], v[96:99]
	v_mfma_f32_16x16x32_bf16 v[92:95], v[162:165], v[210:213], v[92:95]
	v_mfma_f32_16x16x32_bf16 v[80:83], v[152:155], v[214:217], v[80:83]
	v_mfma_f32_16x16x32_bf16 v[76:79], v[162:165], v[214:217], v[76:79]
	v_mfma_f32_16x16x32_bf16 v[120:123], v[170:173], v[186:189], v[120:123]
	v_mfma_f32_16x16x32_bf16 v[116:119], v[178:181], v[186:189], v[116:119]
	v_mfma_f32_16x16x32_bf16 v[104:107], v[170:173], v[190:193], v[104:107]
	v_mfma_f32_16x16x32_bf16 v[100:103], v[178:181], v[190:193], v[100:103]
	v_mfma_f32_16x16x32_bf16 v[88:91], v[170:173], v[202:205], v[88:91]
	v_mfma_f32_16x16x32_bf16 v[84:87], v[178:181], v[202:205], v[84:87]
	v_mfma_f32_16x16x32_bf16 v[72:75], v[170:173], v[206:209], v[72:75]
	v_mfma_f32_16x16x32_bf16 v[68:71], v[178:181], v[206:209], v[68:71]
	v_mfma_f32_16x16x32_bf16 v[120:123], v[174:177], v[194:197], v[120:123]
	v_mfma_f32_16x16x32_bf16 v[116:119], v[182:185], v[194:197], v[116:119]
	v_mfma_f32_16x16x32_bf16 v[104:107], v[174:177], v[198:201], v[104:107]
	v_mfma_f32_16x16x32_bf16 v[100:103], v[182:185], v[198:201], v[100:103]
	v_mfma_f32_16x16x32_bf16 v[88:91], v[174:177], v[210:213], v[88:91]
	v_mfma_f32_16x16x32_bf16 v[84:87], v[182:185], v[210:213], v[84:87]
	v_mfma_f32_16x16x32_bf16 v[72:75], v[174:177], v[214:217], v[72:75]
	v_mfma_f32_16x16x32_bf16 v[68:71], v[182:185], v[214:217], v[68:71]
	s_setprio 0
	s_barrier
	v_lshl_add_u64 v[166:167], s[78:79], 0, v[132:133]
	s_add_i32 s78, s64, s34
	s_mov_b32 m0, s78
	ds_read_b128 v[186:189], v145 offset:16384
	ds_read_b128 v[190:193], v145 offset:18432
	ds_read_b128 v[194:197], v146 offset:16384
	ds_read_b128 v[198:201], v146 offset:18432
	ds_read_b128 v[202:205], v145 offset:20480
	ds_read_b128 v[206:209], v145 offset:22528
	ds_read_b128 v[210:213], v146 offset:20480
	ds_read_b128 v[214:217], v146 offset:22528
	global_load_lds_dwordx4 v[166:167], off
	v_lshl_add_u64 v[218:219], v[166:167], 0, s[10:11]
	s_add_i32 m0, s78, 0x2000
	s_add_i32 s78, s66, s34
	global_load_lds_dwordx4 v[218:219], off
	v_lshl_add_u64 v[218:219], v[166:167], 0, s[14:15]
	s_mov_b32 m0, s78
	s_nop 0
	global_load_lds_dwordx4 v[218:219], off
	v_lshl_add_u64 v[218:219], v[166:167], 0, s[16:17]
	s_add_i32 m0, s78, 0x2000
	s_nop 0
	global_load_lds_dwordx4 v[218:219], off
	s_waitcnt vmcnt(4)
	s_waitcnt lgkmcnt(0)
	s_setprio 1
	s_barrier
	v_mfma_f32_16x16x32_bf16 v[64:67], v[148:151], v[186:189], v[64:67]
	v_mfma_f32_16x16x32_bf16 v[60:63], v[158:161], v[186:189], v[60:63]
	v_mfma_f32_16x16x32_bf16 v[48:51], v[148:151], v[190:193], v[48:51]
	v_mfma_f32_16x16x32_bf16 v[44:47], v[158:161], v[190:193], v[44:47]
	v_mfma_f32_16x16x32_bf16 v[32:35], v[148:151], v[202:205], v[32:35]
	v_mfma_f32_16x16x32_bf16 v[28:31], v[158:161], v[202:205], v[28:31]
	v_mfma_f32_16x16x32_bf16 v[16:19], v[148:151], v[206:209], v[16:19]
	v_mfma_f32_16x16x32_bf16 v[12:15], v[158:161], v[206:209], v[12:15]
	v_mfma_f32_16x16x32_bf16 v[64:67], v[152:155], v[194:197], v[64:67]
	v_mfma_f32_16x16x32_bf16 v[60:63], v[162:165], v[194:197], v[60:63]
	v_mfma_f32_16x16x32_bf16 v[48:51], v[152:155], v[198:201], v[48:51]
	v_mfma_f32_16x16x32_bf16 v[44:47], v[162:165], v[198:201], v[44:47]
	v_mfma_f32_16x16x32_bf16 v[32:35], v[152:155], v[210:213], v[32:35]
	v_mfma_f32_16x16x32_bf16 v[28:31], v[162:165], v[210:213], v[28:31]
	v_mfma_f32_16x16x32_bf16 v[16:19], v[152:155], v[214:217], v[16:19]
	v_mfma_f32_16x16x32_bf16 v[12:15], v[162:165], v[214:217], v[12:15]
	v_mfma_f32_16x16x32_bf16 v[56:59], v[170:173], v[186:189], v[56:59]
	v_mfma_f32_16x16x32_bf16 v[52:55], v[178:181], v[186:189], v[52:55]
	v_mfma_f32_16x16x32_bf16 v[40:43], v[170:173], v[190:193], v[40:43]
	v_mfma_f32_16x16x32_bf16 v[36:39], v[178:181], v[190:193], v[36:39]
	v_mfma_f32_16x16x32_bf16 v[24:27], v[170:173], v[202:205], v[24:27]
	v_mfma_f32_16x16x32_bf16 v[20:23], v[178:181], v[202:205], v[20:23]
	v_mfma_f32_16x16x32_bf16 v[8:11], v[170:173], v[206:209], v[8:11]
	v_mfma_f32_16x16x32_bf16 v[4:7], v[178:181], v[206:209], v[4:7]
	v_mfma_f32_16x16x32_bf16 v[56:59], v[174:177], v[194:197], v[56:59]
	v_mfma_f32_16x16x32_bf16 v[52:55], v[182:185], v[194:197], v[52:55]
	v_mfma_f32_16x16x32_bf16 v[40:43], v[174:177], v[198:201], v[40:43]
	v_mfma_f32_16x16x32_bf16 v[36:39], v[182:185], v[198:201], v[36:39]
	v_mfma_f32_16x16x32_bf16 v[24:27], v[174:177], v[210:213], v[24:27]
	v_mfma_f32_16x16x32_bf16 v[20:23], v[182:185], v[210:213], v[20:23]
	v_mfma_f32_16x16x32_bf16 v[8:11], v[174:177], v[214:217], v[8:11]
	v_mfma_f32_16x16x32_bf16 v[4:7], v[182:185], v[214:217], v[4:7]
	s_setprio 0
	s_barrier
	v_add_u32_e32 v147, s70, v143
	v_add_u32_e32 v152, s70, v144
	ds_read_b128 v[148:151], v147
	ds_read_b128 v[152:155], v152
	v_add_u32_e32 v147, s68, v143
	v_add_u32_e32 v162, s68, v144
	ds_read_b128 v[158:161], v147
	ds_read_b128 v[162:165], v162
	v_add_u32_e32 v147, s71, v143
	v_add_u32_e32 v169, s71, v144
	ds_read_b128 v[170:173], v147
	ds_read_b128 v[174:177], v169
	v_add_u32_e32 v147, s69, v143
	v_add_u32_e32 v169, s69, v144
	ds_read_b128 v[178:181], v147
	ds_read_b128 v[182:185], v169
	s_mov_b32 m0, s35
	v_lshl_add_u64 v[218:219], s[58:59], 0, v[0:1]
	ds_read_b128 v[186:189], v145 offset:32768
	ds_read_b128 v[190:193], v145 offset:34816
	ds_read_b128 v[194:197], v146 offset:32768
	ds_read_b128 v[198:201], v146 offset:34816
	ds_read_b128 v[202:205], v145 offset:36864
	ds_read_b128 v[206:209], v145 offset:38912
	ds_read_b128 v[210:213], v146 offset:36864
	ds_read_b128 v[214:217], v146 offset:38912
	global_load_lds_dwordx4 v[218:219], off
	v_lshl_add_u64 v[220:221], v[218:219], 0, s[20:21]
	s_mov_b32 m0, s39
	s_nop 0
	global_load_lds_dwordx4 v[220:221], off
	v_lshl_add_u64 v[220:221], v[218:219], 0, s[10:11]
	s_mov_b32 m0, s60
	v_lshl_add_u64 v[218:219], v[218:219], 0, s[22:23]
	global_load_lds_dwordx4 v[220:221], off
	s_mov_b32 m0, s61
	s_nop 0
	global_load_lds_dwordx4 v[218:219], off
	s_waitcnt vmcnt(8)
	s_waitcnt lgkmcnt(0)
	s_setprio 1
	s_barrier
	v_mfma_f32_16x16x32_bf16 v[128:131], v[148:151], v[186:189], v[128:131]
	v_mfma_f32_16x16x32_bf16 v[124:127], v[158:161], v[186:189], v[124:127]
	v_mfma_f32_16x16x32_bf16 v[112:115], v[148:151], v[190:193], v[112:115]
	v_mfma_f32_16x16x32_bf16 v[108:111], v[158:161], v[190:193], v[108:111]
	v_mfma_f32_16x16x32_bf16 v[96:99], v[148:151], v[202:205], v[96:99]
	v_mfma_f32_16x16x32_bf16 v[92:95], v[158:161], v[202:205], v[92:95]
	v_mfma_f32_16x16x32_bf16 v[80:83], v[148:151], v[206:209], v[80:83]
	v_mfma_f32_16x16x32_bf16 v[76:79], v[158:161], v[206:209], v[76:79]
	v_mfma_f32_16x16x32_bf16 v[128:131], v[152:155], v[194:197], v[128:131]
	v_mfma_f32_16x16x32_bf16 v[124:127], v[162:165], v[194:197], v[124:127]
	v_mfma_f32_16x16x32_bf16 v[112:115], v[152:155], v[198:201], v[112:115]
	v_mfma_f32_16x16x32_bf16 v[108:111], v[162:165], v[198:201], v[108:111]
	v_mfma_f32_16x16x32_bf16 v[96:99], v[152:155], v[210:213], v[96:99]
	v_mfma_f32_16x16x32_bf16 v[92:95], v[162:165], v[210:213], v[92:95]
	v_mfma_f32_16x16x32_bf16 v[80:83], v[152:155], v[214:217], v[80:83]
	v_mfma_f32_16x16x32_bf16 v[76:79], v[162:165], v[214:217], v[76:79]
	v_mfma_f32_16x16x32_bf16 v[120:123], v[170:173], v[186:189], v[120:123]
	v_mfma_f32_16x16x32_bf16 v[116:119], v[178:181], v[186:189], v[116:119]
	v_mfma_f32_16x16x32_bf16 v[104:107], v[170:173], v[190:193], v[104:107]
	v_mfma_f32_16x16x32_bf16 v[100:103], v[178:181], v[190:193], v[100:103]
	v_mfma_f32_16x16x32_bf16 v[88:91], v[170:173], v[202:205], v[88:91]
	v_mfma_f32_16x16x32_bf16 v[84:87], v[178:181], v[202:205], v[84:87]
	v_mfma_f32_16x16x32_bf16 v[72:75], v[170:173], v[206:209], v[72:75]
	v_mfma_f32_16x16x32_bf16 v[68:71], v[178:181], v[206:209], v[68:71]
	v_mfma_f32_16x16x32_bf16 v[120:123], v[174:177], v[194:197], v[120:123]
	v_mfma_f32_16x16x32_bf16 v[116:119], v[182:185], v[194:197], v[116:119]
	v_mfma_f32_16x16x32_bf16 v[104:107], v[174:177], v[198:201], v[104:107]
	v_mfma_f32_16x16x32_bf16 v[100:103], v[182:185], v[198:201], v[100:103]
	v_mfma_f32_16x16x32_bf16 v[88:91], v[174:177], v[210:213], v[88:91]
	v_mfma_f32_16x16x32_bf16 v[84:87], v[182:185], v[210:213], v[84:87]
	v_mfma_f32_16x16x32_bf16 v[72:75], v[174:177], v[214:217], v[72:75]
	v_mfma_f32_16x16x32_bf16 v[68:71], v[182:185], v[214:217], v[68:71]
	s_setprio 0
	s_barrier
	s_add_i32 s58, s70, s34
	v_lshl_add_u64 v[218:219], v[166:167], 0, s[24:25]
	s_mov_b32 m0, s58
	ds_read_b128 v[186:189], v145 offset:49152
	ds_read_b128 v[190:193], v145 offset:51200
	ds_read_b128 v[194:197], v146 offset:49152
	ds_read_b128 v[198:201], v146 offset:51200
	ds_read_b128 v[202:205], v145 offset:53248
	ds_read_b128 v[206:209], v145 offset:55296
	ds_read_b128 v[210:213], v146 offset:53248
	ds_read_b128 v[214:217], v146 offset:55296
	global_load_lds_dwordx4 v[218:219], off
	v_lshl_add_u64 v[218:219], v[166:167], 0, s[28:29]
	s_add_i32 m0, s58, 0x2000
	s_add_i32 s58, s71, s34
	global_load_lds_dwordx4 v[218:219], off
	v_lshl_add_u64 v[218:219], v[166:167], 0, s[36:37]
	s_mov_b32 m0, s58
	v_lshl_add_u64 v[166:167], v[166:167], 0, s[40:41]
	global_load_lds_dwordx4 v[218:219], off
	s_add_i32 m0, s58, 0x2000
	s_nop 0
	global_load_lds_dwordx4 v[166:167], off
	s_waitcnt vmcnt(4)
	s_waitcnt lgkmcnt(0)
	s_setprio 1
	s_barrier
	v_mfma_f32_16x16x32_bf16 v[64:67], v[148:151], v[186:189], v[64:67]
	v_mfma_f32_16x16x32_bf16 v[60:63], v[158:161], v[186:189], v[60:63]
	v_mfma_f32_16x16x32_bf16 v[48:51], v[148:151], v[190:193], v[48:51]
	v_mfma_f32_16x16x32_bf16 v[44:47], v[158:161], v[190:193], v[44:47]
	v_mfma_f32_16x16x32_bf16 v[32:35], v[148:151], v[202:205], v[32:35]
	v_mfma_f32_16x16x32_bf16 v[28:31], v[158:161], v[202:205], v[28:31]
	v_mfma_f32_16x16x32_bf16 v[16:19], v[148:151], v[206:209], v[16:19]
	v_mfma_f32_16x16x32_bf16 v[12:15], v[158:161], v[206:209], v[12:15]
	v_mfma_f32_16x16x32_bf16 v[64:67], v[152:155], v[194:197], v[64:67]
	v_mfma_f32_16x16x32_bf16 v[60:63], v[162:165], v[194:197], v[60:63]
	v_mfma_f32_16x16x32_bf16 v[48:51], v[152:155], v[198:201], v[48:51]
	v_mfma_f32_16x16x32_bf16 v[44:47], v[162:165], v[198:201], v[44:47]
	v_mfma_f32_16x16x32_bf16 v[32:35], v[152:155], v[210:213], v[32:35]
	v_mfma_f32_16x16x32_bf16 v[28:31], v[162:165], v[210:213], v[28:31]
	v_mfma_f32_16x16x32_bf16 v[16:19], v[152:155], v[214:217], v[16:19]
	v_mfma_f32_16x16x32_bf16 v[12:15], v[162:165], v[214:217], v[12:15]
	v_mfma_f32_16x16x32_bf16 v[56:59], v[170:173], v[186:189], v[56:59]
	v_mfma_f32_16x16x32_bf16 v[52:55], v[178:181], v[186:189], v[52:55]
	v_mfma_f32_16x16x32_bf16 v[40:43], v[170:173], v[190:193], v[40:43]
	v_mfma_f32_16x16x32_bf16 v[36:39], v[178:181], v[190:193], v[36:39]
	v_mfma_f32_16x16x32_bf16 v[24:27], v[170:173], v[202:205], v[24:27]
	v_mfma_f32_16x16x32_bf16 v[20:23], v[178:181], v[202:205], v[20:23]
	v_mfma_f32_16x16x32_bf16 v[8:11], v[170:173], v[206:209], v[8:11]
	v_mfma_f32_16x16x32_bf16 v[4:7], v[178:181], v[206:209], v[4:7]
	v_mfma_f32_16x16x32_bf16 v[56:59], v[174:177], v[194:197], v[56:59]
	v_mfma_f32_16x16x32_bf16 v[52:55], v[182:185], v[194:197], v[52:55]
	v_mfma_f32_16x16x32_bf16 v[40:43], v[174:177], v[198:201], v[40:43]
	v_mfma_f32_16x16x32_bf16 v[36:39], v[182:185], v[198:201], v[36:39]
	v_mfma_f32_16x16x32_bf16 v[24:27], v[174:177], v[210:213], v[24:27]
	v_mfma_f32_16x16x32_bf16 v[20:23], v[182:185], v[210:213], v[20:23]
	v_mfma_f32_16x16x32_bf16 v[8:11], v[174:177], v[214:217], v[8:11]
	v_mfma_f32_16x16x32_bf16 v[4:7], v[182:185], v[214:217], v[4:7]
	s_setprio 0
	s_barrier
	s_add_i32 s77, s77, 2
	s_add_u32 s56, s56, 0x100
	s_addc_u32 s57, s57, 0
	s_cmp_gt_u32 s77, 61
	s_cbranch_scc0 .LBB0_1371
	s_add_u32 s56, s53, 0xffffff00
	s_addc_u32 s57, s72, -1
	s_andn2_b64 vcc, exec, s[6:7]
	s_cbranch_vccnz .LBB0_1362
	v_mov_b32_e32 v4, 0
	s_mov_b32 s0, s48
	s_mov_b32 s8, s50
	s_mov_b64 s[18:19], s[54:55]
	s_mov_b32 s63, s52
	v_mov_b32_e32 v5, v4
	v_mov_b32_e32 v6, v4
	v_mov_b32_e32 v7, v4
	v_mov_b32_e32 v8, v4
	v_mov_b32_e32 v9, v4
	v_mov_b32_e32 v10, v4
	v_mov_b32_e32 v11, v4
	v_mov_b32_e32 v20, v4
	v_mov_b32_e32 v21, v4
	v_mov_b32_e32 v22, v4
	v_mov_b32_e32 v23, v4
	v_mov_b32_e32 v24, v4
	v_mov_b32_e32 v25, v4
	v_mov_b32_e32 v26, v4
	v_mov_b32_e32 v27, v4
	v_mov_b32_e32 v36, v4
	v_mov_b32_e32 v37, v4
	v_mov_b32_e32 v38, v4
	v_mov_b32_e32 v39, v4
	v_mov_b32_e32 v40, v4
	v_mov_b32_e32 v41, v4
	v_mov_b32_e32 v42, v4
	v_mov_b32_e32 v43, v4
	v_mov_b32_e32 v52, v4
	v_mov_b32_e32 v53, v4
	v_mov_b32_e32 v54, v4
	v_mov_b32_e32 v55, v4
	v_mov_b32_e32 v56, v4
	v_mov_b32_e32 v57, v4
	v_mov_b32_e32 v58, v4
	v_mov_b32_e32 v59, v4
	v_mov_b32_e32 v12, v4
	v_mov_b32_e32 v13, v4
	v_mov_b32_e32 v14, v4
	v_mov_b32_e32 v15, v4
	v_mov_b32_e32 v16, v4
	v_mov_b32_e32 v17, v4
	v_mov_b32_e32 v18, v4
	v_mov_b32_e32 v19, v4
	v_mov_b32_e32 v28, v4
	v_mov_b32_e32 v29, v4
	v_mov_b32_e32 v30, v4
	v_mov_b32_e32 v31, v4
	v_mov_b32_e32 v32, v4
	v_mov_b32_e32 v33, v4
	v_mov_b32_e32 v34, v4
	v_mov_b32_e32 v35, v4
	v_mov_b32_e32 v44, v4
	v_mov_b32_e32 v45, v4
	v_mov_b32_e32 v46, v4
	v_mov_b32_e32 v47, v4
	v_mov_b32_e32 v48, v4
	v_mov_b32_e32 v49, v4
	v_mov_b32_e32 v50, v4
	v_mov_b32_e32 v51, v4
	v_mov_b32_e32 v60, v4
	v_mov_b32_e32 v61, v4
	v_mov_b32_e32 v62, v4
	v_mov_b32_e32 v63, v4
	v_mov_b32_e32 v64, v4
	v_mov_b32_e32 v65, v4
	v_mov_b32_e32 v66, v4
	v_mov_b32_e32 v67, v4
	v_mov_b32_e32 v68, v4
	v_mov_b32_e32 v69, v4
	v_mov_b32_e32 v70, v4
	v_mov_b32_e32 v71, v4
	v_mov_b32_e32 v72, v4
	v_mov_b32_e32 v73, v4
	v_mov_b32_e32 v74, v4
	v_mov_b32_e32 v75, v4
	v_mov_b32_e32 v84, v4
	v_mov_b32_e32 v85, v4
	v_mov_b32_e32 v86, v4
	v_mov_b32_e32 v87, v4
	v_mov_b32_e32 v88, v4
	v_mov_b32_e32 v89, v4
	v_mov_b32_e32 v90, v4
	v_mov_b32_e32 v91, v4
	v_mov_b32_e32 v100, v4
	v_mov_b32_e32 v101, v4
	v_mov_b32_e32 v102, v4
	v_mov_b32_e32 v103, v4
	v_mov_b32_e32 v104, v4
	v_mov_b32_e32 v105, v4
	v_mov_b32_e32 v106, v4
	v_mov_b32_e32 v107, v4
	v_mov_b32_e32 v116, v4
	v_mov_b32_e32 v117, v4
	v_mov_b32_e32 v118, v4
	v_mov_b32_e32 v119, v4
	v_mov_b32_e32 v120, v4
	v_mov_b32_e32 v121, v4
	v_mov_b32_e32 v122, v4
	v_mov_b32_e32 v123, v4
	v_mov_b32_e32 v76, v4
	v_mov_b32_e32 v77, v4
	v_mov_b32_e32 v78, v4
	v_mov_b32_e32 v79, v4
	v_mov_b32_e32 v80, v4
	v_mov_b32_e32 v81, v4
	v_mov_b32_e32 v82, v4
	v_mov_b32_e32 v83, v4
	v_mov_b32_e32 v92, v4
	v_mov_b32_e32 v93, v4
	v_mov_b32_e32 v94, v4
	v_mov_b32_e32 v95, v4
	v_mov_b32_e32 v96, v4
	v_mov_b32_e32 v97, v4
	v_mov_b32_e32 v98, v4
	v_mov_b32_e32 v99, v4
	v_mov_b32_e32 v108, v4
	v_mov_b32_e32 v109, v4
	v_mov_b32_e32 v110, v4
	v_mov_b32_e32 v111, v4
	v_mov_b32_e32 v112, v4
	v_mov_b32_e32 v113, v4
	v_mov_b32_e32 v114, v4
	v_mov_b32_e32 v115, v4
	v_mov_b32_e32 v124, v4
	v_mov_b32_e32 v125, v4
	v_mov_b32_e32 v126, v4
	v_mov_b32_e32 v127, v4
	v_mov_b32_e32 v128, v4
	v_mov_b32_e32 v129, v4
	v_mov_b32_e32 v130, v4
	v_mov_b32_e32 v131, v4
	s_andn2_b64 vcc, exec, s[4:5]
	s_cbranch_vccnz .LBB0_1363
